# comb1 + conv row fast path + gMLP: LN/out-norm tables, gate weights and gate bias exchanged through LDS (fewer vector-memory instructions)
# speedup vs baseline: 1.0092x; 1.0056x over previous
; #define LAS __attribute__((address_space(3)))
; __global__ void __launch_bounds__(NTHR, 2) fwd_megakernel(Args args) {
;     ...
;             const int tc0 = (su >> 2) * 128, qi = su & 3, i0 = 32 * qi, J = qi < 2 ? 64 : 128;
;             constexpr int LDB = 136;
;             LAS bf16_t* Bt = (LAS bf16_t*)lds;
;             LAS f32x2* st = (LAS f32x2*)(lds + 2 * 128 * LDB * 2);
;             LAS float* red = (LAS float*)(lds + 2 * 128 * LDB * 2 + 1024);
;             if (tid < J) { const f32x4* p = (const f32x4*)(VSTAT + (size_t)(tc0 + tid) * 32); float s1 = 0.f, s2 = 0.f;
; #pragma unroll
;                 for (int j = 0; j < 8; ++j) { const f32x4 v = p[j]; s1 += v[0] + v[2]; s2 += v[1] + v[3]; }
;                 const float mean = s1 * (1.0f / CCH), var = fmaxf(s2 * (1.0f / CCH) - mean * mean, 0.f); st[tid] = (f32x2){mean, rsqrtf(var + LN_EPS)}; }
;             const int mb = wave & 1, nq = wave >> 1, fr = lane & 15, fq = lane >> 4;
;             const int trow = tc0 + i0 + 16 * mb + fr;
;             const float* lng = KIN(I_SGU_LN_G); const float* lnb = KIN(I_SGU_LN_B); const float* sgb = KIN(I_SGU_B);
;             const int c8 = tid & 15, jb = tid >> 4, nk = J / 32;
;             u32x4 pv[4]; f32x4 pg0, pg1, pb0, pb1; bf16x8 pw[4]; u32x2 pu0, pu1; float pbs;
;     ...
;             f32x4 yv[8][2]; float ss = 0.f;
;             SGU_PREFETCH(0);
;             __syncthreads();
; #pragma unroll
;             for (int h = 0; h < 8; ++h) {
;                 LAS bf16_t* Bc = Bt + (h & 1) * (128 * LDB);
; #pragma unroll
;                 for (int k = 0; k < 4; ++k) if (k < nk) { const int j = jb + 32 * k; const u32x4 v = pv[k]; const f32x2 ms = st[j];
;                     const f32x4 x0 = (f32x4){bf_lo(v.x), bf_hi(v.x), bf_lo(v.y), bf_hi(v.y)}, x1 = (f32x4){bf_lo(v.z), bf_hi(v.z), bf_lo(v.w), bf_hi(v.w)};
;                     const f32x4 y0 = (x0 - ms.x) * ms.y * pg0 + pb0, y1 = (x1 - ms.x) * ms.y * pg1 + pb1;
;                     LAS bf16_t* d = Bc + (c8 * 8) * LDB + (j ^ (8 * c8));
;                     const unsigned p0 = cvt_pk_bf16(y0[0], y0[1]), p1 = cvt_pk_bf16(y0[2], y0[3]), p2 = cvt_pk_bf16(y1[0], y1[1]), p3 = cvt_pk_bf16(y1[2], y1[3]);
;                     d[0 * LDB] = (bf16_t)(p0 & 0xffffu); d[1 * LDB] = (bf16_t)(p0 >> 16); d[2 * LDB] = (bf16_t)(p1 & 0xffffu); d[3 * LDB] = (bf16_t)(p1 >> 16);
.LBB0_657:
	v_readlane_b32 s2, v254, 3
	s_add_i32 s11, 0, 0x11000
	s_bfe_u32 s4, s2, 0x10006
	s_lshr_b32 s5, s2, 7
	v_and_b32_e32 v2, 15, v221
	s_add_u32 s2, s0, s42
	v_mov_b32_e32 v121, 0
	v_lshl_or_b32 v155, s4, 4, v2
	s_addc_u32 s3, s1, s43
	v_and_b32_e32 v0, 48, v220
	v_mov_b32_e32 v1, v121
	s_lshl_b32 s4, s4, 8
	s_load_dwordx4 s[24:27], s[2:3], 0x58
	s_load_dwordx2 s[20:21], s[2:3], 0x70
	s_load_dwordx2 s[100:101], s[2:3], 0x80
	v_lshl_add_u64 v[0:1], s[14:15], 0, v[0:1]
	s_mov_b64 s[2:3], 0xbc00000
	s_add_i32 s4, s4, 0
	v_lshl_add_u64 v[128:129], v[0:1], 0, s[2:3]
	s_lshl_b32 s18, s5, 5
	v_mov_b32_e32 v0, 0x68
	s_add_i32 s4, s4, 0x11400
	s_lshl_b32 s5, s5, 6
	v_lshlrev_b32_e32 v120, 4, v2
	v_bitop3_b32 v7, s18, v0, v2 bitop3:0xc8
	s_add_i32 s23, s4, s5
	v_lshlrev_b32_e32 v0, 2, v2
	v_lshrrev_b32_e32 v3, 4, v220
	v_lshl_add_u64 v[122:123], s[36:37], 0, v[120:121]
	v_lshlrev_b32_e32 v120, 5, v2
	v_add_u32_e32 v175, s4, v0
	s_add_u32 s4, s88, s5
	s_waitcnt lgkmcnt(0)
	v_lshl_add_u64 v[124:125], s[24:25], 0, v[120:121]
	v_lshl_add_u64 v[126:127], s[26:27], 0, v[120:121]
	v_lshlrev_b32_e32 v120, 3, v3
	s_addc_u32 s5, s89, 0
	v_lshrrev_b32_e32 v163, 4, v221
	v_lshlrev_b32_e32 v4, 3, v2
	v_lshl_add_u64 v[130:131], s[4:5], 0, v[120:121]
	s_movk_i32 s4, 0x880
	v_or_b32_e32 v1, s18, v2
	v_add_u32_e32 v169, s23, v0
	v_lshl_or_b32 v0, v3, 2, s18
	v_mad_u32_u24 v2, v2, s4, 0
	v_xor_b32_e32 v3, v163, v4
	v_lshl_add_u32 v186, v3, 1, v2
	v_add_u32_e32 v3, 32, v163
	v_lshl_add_u32 v187, v3, 3, s11
	v_xor_b32_e32 v3, v3, v4
	v_lshl_add_u32 v188, v3, 1, v2
	v_or_b32_e32 v3, 64, v163
	v_lshl_add_u32 v189, v3, 3, s11
	v_bitop3_b32 v3, v163, v4, 64 bitop3:0x36
	s_movk_i32 s2, 0x110
	v_lshl_add_u32 v190, v3, 1, v2
	v_add_u32_e32 v3, 0x60, v163
	v_mul_lo_u32 v6, v1, s2
	s_movk_i32 s19, 0x68
	s_movk_i32 s22, 0x78
	v_lshl_add_u32 v191, v3, 3, s11
	v_xor_b32_e32 v3, v3, v4
	v_or_b32_e32 v5, 16, v1
	v_bitop3_b32 v8, v1, s22, 16 bitop3:0xc8
	v_lshl_add_u32 v192, v3, 1, v2
	v_add_u32_e32 v2, 0, v6
	v_bitop3_b32 v1, v120, v1, s19 bitop3:0x78
	v_add_u32_e32 v3, 0x1100, v2
	v_lshl_add_u32 v193, v1, 1, v2
	v_bitop3_b32 v1, v120, v5, s22 bitop3:0x78
	v_lshl_add_u32 v194, v1, 1, v3
	v_bitop3_b32 v1, v120, v7, 32 bitop3:0x36
	v_lshl_add_u32 v195, v1, 1, v2
	v_bitop3_b32 v1, v120, v8, 32 bitop3:0x36
	v_lshl_add_u32 v196, v1, 1, v3
	v_bitop3_b32 v1, v120, v7, 64 bitop3:0x36
	s_movk_i32 s4, 0x60
	v_lshl_add_u32 v197, v1, 1, v2
	v_bitop3_b32 v1, v120, v8, 64 bitop3:0x36
	v_lshl_add_u32 v198, v1, 1, v3
	v_bitop3_b32 v1, v120, v7, s4 bitop3:0x36
	v_lshl_add_u32 v199, v1, 1, v2
	v_bitop3_b32 v1, v120, v8, s4 bitop3:0x36
	v_lshlrev_b32_e32 v120, 1, v0
	v_lshl_add_u32 v137, v221, 3, s11
	v_cmp_gt_u32_e64 s[2:3], 16, v220
	v_lshl_add_u32 v181, v163, 3, s11
	v_lshl_add_u32 v200, v1, 1, v3
	v_lshl_add_u64 v[132:133], s[6:7], 0, v[120:121]
	s_lshl_b32 s23, s10, 5
	s_lshl_b32 s56, s34, 5
	s_mov_b32 s22, 0x3a800000
	s_mov_b32 s57, 0x800000
	v_and_b32_e32 v238, 0xff, v221
	v_lshlrev_b32_e32 v238, 4, v238
	v_mov_b32_e32 v239, 0
	v_lshl_add_u64 v[214:215], s[100:101], 0, v[238:239]
	v_cmp_gt_u32_e32 vcc, 0x100, v221
	v_mov_b32_e32 v240, s26
	v_mov_b32_e32 v241, s27
	v_mov_b32_e32 v242, s24
	v_mov_b32_e32 v243, s25
	s_nop 1
	v_cndmask_b32_e32 v240, v240, v242, vcc
	v_cndmask_b32_e32 v241, v241, v243, vcc
	v_lshl_add_u64 v[212:213], v[240:241], 0, v[238:239]
	v_lshl_add_u64 v[240:241], s[20:21], 0, v[238:239]
	v_cmp_gt_u32_e32 vcc, 0x100, v221
	s_nop 1
	v_cndmask_b32_e32 v214, v240, v214, vcc
	v_cndmask_b32_e32 v215, v241, v215, vcc
	v_lshrrev_b32_e32 v228, 4, v221
	v_mul_u32_u24_e32 v228, 0x110, v228
	v_and_b32_e32 v229, 15, v221
	v_lshl_add_u32 v228, v229, 4, v228
	v_add_u32_e32 v228, 0x15600, v228
	v_mul_u32_u24_e32 v229, 0x110, v155
	v_and_b32_e32 v240, 48, v220
	v_add3_u32 v229, v229, v240, 0
	v_add_u32_e32 v229, 0x15600, v229
	v_and_b32_e32 v203, 15, v221
	v_lshlrev_b32_e32 v203, 5, v203
	v_add_u32_e32 v203, 0x11600, v203
	s_mov_b64 s[24:25], 0x10000
	v_mov_b32_e32 v201, 0x358637bd
	v_lshlrev_b32_e32 v202, 2, v0
	s_nop 0
	s_mov_b32 s58, s10
	s_branch .LBB0_659
.LBB0_658:
	s_or_b64 exec, exec, s[4:5]
	s_waitcnt lgkmcnt(0)
	v_add_u32_e32 v252, 0x13600, v202
	ds_read_b128 v[90:93], v252
	ds_read_b128 v[94:97], v252 offset:64
	ds_read_b128 v[98:101], v252 offset:512
	ds_read_b128 v[102:105], v252 offset:576
	ds_read_b128 v[106:109], v252 offset:1024
	ds_read_b128 v[110:113], v252 offset:1088
	ds_read_b128 v[114:117], v252 offset:1536
	ds_read_b128 v[138:141], v252 offset:1600
	ds_read_b128 v[142:145], v252 offset:2048
	ds_read_b128 v[146:149], v252 offset:2112
	ds_read_b128 v[150:153], v252 offset:2560
	ds_read_b128 v[230:233], v252 offset:2624
	ds_read_b128 v[234:237], v252 offset:3072
	ds_read_b128 v[238:241], v252 offset:3136
	ds_read_b128 v[244:247], v252 offset:3584
	ds_read_b128 v[248:251], v252 offset:3648
	s_barrier
; __device__ __forceinline__ unsigned cvt_pk_bf16(float lo, float hi) { unsigned r; asm volatile("v_cvt_pk_bf16_f32 %0, %1, %2" : "=v"(r) : "v"(lo), "v"(hi)); return r; }
; #define KIN(i) (*(const float* const __attribute__((address_space(4)))*)(kp + kz + 8 * (i)))
; __global__ void __launch_bounds__(NTHR, 2) fwd_megakernel(Args args) {
;     ...
;             ss += __shfl_xor(ss, 16); ss += __shfl_xor(ss, 32);
;             if (fq == 0) red[(mb * 4 + nq) * 16 + fr] = ss;
;             __syncthreads();
;             const float tot = (red[(mb * 4 + 0) * 16 + fr] + red[(mb * 4 + 1) * 16 + fr]) + (red[(mb * 4 + 2) * 16 + fr] + red[(mb * 4 + 3) * 16 + fr]);
;             const float r2 = rsqrtf(tot * (1.0f / CCH) + RMS_EPS);
; #pragma unroll
;             for (int h = 0; h < 8; ++h)
; #pragma unroll
;                 for (int nb = 0; nb < 2; ++nb) { const int ch = h * 128 + 32 * nq + 16 * nb + 4 * fq; const f32x4 gg = *(const f32x4*)(KIN(I_OUT_NORM_SGU) + ch); const f32x4 y = yv[h][nb] * r2 * gg;
;                     u32x2 w; w.x = cvt_pk_bf16(y[0], y[1]); w.y = cvt_pk_bf16(y[2], y[3]); *(u32x2*)(Y + (size_t)trow * D + CCH + ch) = w; }
	s_add_i32 s58, s58, s34
	s_add_i32 s23, s23, s56
	s_cmpk_lt_i32 s58, 0x100
	ds_read2_b32 v[72:73], v175 offset1:16
	ds_read2_b32 v[74:75], v175 offset0:32 offset1:48
	s_waitcnt lgkmcnt(1)
	v_mov_b32_e32 v78, v72
	s_waitcnt lgkmcnt(0)
	v_mov_b32_e32 v79, v74
	v_mov_b32_e32 v74, v73
	v_pk_add_f32 v[72:73], v[78:79], v[74:75]
	s_nop 0
	v_add_f32_e32 v72, v72, v73
	v_fmamk_f32 v72, v72, 0x3a800000, v201
	v_mul_f32_e32 v73, 0x4b800000, v72
	v_cmp_gt_f32_e32 vcc, s57, v72
	s_nop 1
	v_cndmask_b32_e32 v72, v72, v73, vcc
	v_rsq_f32_e32 v74, v72
	v_lshlrev_b64 v[72:73], 12, v[134:135]
	v_lshl_add_u64 v[72:73], v[132:133], 0, v[72:73]
	v_mul_f32_e32 v75, 0x45800000, v74
	v_cndmask_b32_e32 v74, v74, v75, vcc
	v_pk_mul_f32 v[0:1], v[74:75], v[14:15] op_sel_hi:[0,1]
	v_pk_mul_f32 v[2:3], v[74:75], v[12:13] op_sel_hi:[0,1]
	v_pk_mul_f32 v[0:1], v[90:91], v[0:1]
	v_pk_mul_f32 v[2:3], v[92:93], v[2:3]
	v_cvt_pk_bf16_f32 v0, v0, v1
	v_cvt_pk_bf16_f32 v1, v2, v3
	global_store_dwordx2 v[72:73], v[0:1], off offset:2048
	v_pk_mul_f32 v[4:5], v[74:75], v[10:11] op_sel_hi:[0,1]
	v_pk_mul_f32 v[6:7], v[74:75], v[8:9] op_sel_hi:[0,1]
	v_pk_mul_f32 v[4:5], v[94:95], v[4:5]
	v_pk_mul_f32 v[6:7], v[96:97], v[6:7]
	v_cvt_pk_bf16_f32 v4, v4, v5
	v_cvt_pk_bf16_f32 v5, v6, v7
	global_store_dwordx2 v[72:73], v[4:5], off offset:2080
	v_pk_mul_f32 v[0:1], v[74:75], v[80:81] op_sel_hi:[0,1]
	v_pk_mul_f32 v[2:3], v[74:75], v[20:21] op_sel_hi:[0,1]
	v_pk_mul_f32 v[0:1], v[98:99], v[0:1]
	v_pk_mul_f32 v[2:3], v[100:101], v[2:3]
	v_cvt_pk_bf16_f32 v0, v0, v1
	v_cvt_pk_bf16_f32 v1, v2, v3
	global_store_dwordx2 v[72:73], v[0:1], off offset:2304
	v_pk_mul_f32 v[4:5], v[74:75], v[18:19] op_sel_hi:[0,1]
	v_pk_mul_f32 v[6:7], v[74:75], v[16:17] op_sel_hi:[0,1]
	v_pk_mul_f32 v[4:5], v[102:103], v[4:5]
	v_pk_mul_f32 v[6:7], v[104:105], v[6:7]
	v_cvt_pk_bf16_f32 v4, v4, v5
	v_cvt_pk_bf16_f32 v5, v6, v7
	global_store_dwordx2 v[72:73], v[4:5], off offset:2336
	v_pk_mul_f32 v[0:1], v[74:75], v[30:31] op_sel_hi:[0,1]
	v_pk_mul_f32 v[2:3], v[74:75], v[28:29] op_sel_hi:[0,1]
	v_pk_mul_f32 v[0:1], v[106:107], v[0:1]
	v_pk_mul_f32 v[2:3], v[108:109], v[2:3]
	v_cvt_pk_bf16_f32 v0, v0, v1
	v_cvt_pk_bf16_f32 v1, v2, v3
	global_store_dwordx2 v[72:73], v[0:1], off offset:2560
	v_pk_mul_f32 v[4:5], v[74:75], v[24:25] op_sel_hi:[0,1]
	v_pk_mul_f32 v[6:7], v[74:75], v[22:23] op_sel_hi:[0,1]
	v_pk_mul_f32 v[4:5], v[110:111], v[4:5]
	v_pk_mul_f32 v[6:7], v[112:113], v[6:7]
	v_cvt_pk_bf16_f32 v4, v4, v5
	v_cvt_pk_bf16_f32 v5, v6, v7
	global_store_dwordx2 v[72:73], v[4:5], off offset:2592
	v_pk_mul_f32 v[0:1], v[74:75], v[46:47] op_sel_hi:[0,1]
	v_pk_mul_f32 v[2:3], v[74:75], v[44:45] op_sel_hi:[0,1]
	v_pk_mul_f32 v[0:1], v[114:115], v[0:1]
	v_pk_mul_f32 v[2:3], v[116:117], v[2:3]
	v_cvt_pk_bf16_f32 v0, v0, v1
	v_cvt_pk_bf16_f32 v1, v2, v3
	global_store_dwordx2 v[72:73], v[0:1], off offset:2816
	v_pk_mul_f32 v[4:5], v[74:75], v[40:41] op_sel_hi:[0,1]
	v_pk_mul_f32 v[6:7], v[74:75], v[26:27] op_sel_hi:[0,1]
	v_pk_mul_f32 v[4:5], v[138:139], v[4:5]
	v_pk_mul_f32 v[6:7], v[140:141], v[6:7]
	v_cvt_pk_bf16_f32 v4, v4, v5
	v_cvt_pk_bf16_f32 v5, v6, v7
	global_store_dwordx2 v[72:73], v[4:5], off offset:2848
	v_pk_mul_f32 v[0:1], v[74:75], v[82:83] op_sel_hi:[0,1]
	v_pk_mul_f32 v[2:3], v[74:75], v[52:53] op_sel_hi:[0,1]
	v_pk_mul_f32 v[0:1], v[142:143], v[0:1]
	v_pk_mul_f32 v[2:3], v[144:145], v[2:3]
	v_cvt_pk_bf16_f32 v0, v0, v1
	v_cvt_pk_bf16_f32 v1, v2, v3
	global_store_dwordx2 v[72:73], v[0:1], off offset:3072
	v_pk_mul_f32 v[4:5], v[74:75], v[48:49] op_sel_hi:[0,1]
	v_pk_mul_f32 v[6:7], v[74:75], v[42:43] op_sel_hi:[0,1]
	v_pk_mul_f32 v[4:5], v[146:147], v[4:5]
	v_pk_mul_f32 v[6:7], v[148:149], v[6:7]
	v_cvt_pk_bf16_f32 v4, v4, v5
	v_cvt_pk_bf16_f32 v5, v6, v7
	global_store_dwordx2 v[72:73], v[4:5], off offset:3104
	v_pk_mul_f32 v[0:1], v[74:75], v[84:85] op_sel_hi:[0,1]
	v_pk_mul_f32 v[2:3], v[74:75], v[60:61] op_sel_hi:[0,1]
	v_pk_mul_f32 v[0:1], v[150:151], v[0:1]
	v_pk_mul_f32 v[2:3], v[152:153], v[2:3]
	v_cvt_pk_bf16_f32 v0, v0, v1
	v_cvt_pk_bf16_f32 v1, v2, v3
	global_store_dwordx2 v[72:73], v[0:1], off offset:3328
	v_pk_mul_f32 v[4:5], v[74:75], v[58:59] op_sel_hi:[0,1]
	v_pk_mul_f32 v[6:7], v[74:75], v[54:55] op_sel_hi:[0,1]
	v_pk_mul_f32 v[4:5], v[230:231], v[4:5]
	v_pk_mul_f32 v[6:7], v[232:233], v[6:7]
	v_cvt_pk_bf16_f32 v4, v4, v5
	v_cvt_pk_bf16_f32 v5, v6, v7
	global_store_dwordx2 v[72:73], v[4:5], off offset:3360
	v_pk_mul_f32 v[0:1], v[74:75], v[70:71] op_sel_hi:[0,1]
	v_pk_mul_f32 v[2:3], v[74:75], v[68:69] op_sel_hi:[0,1]
	v_pk_mul_f32 v[0:1], v[234:235], v[0:1]
	v_pk_mul_f32 v[2:3], v[236:237], v[2:3]
	v_cvt_pk_bf16_f32 v0, v0, v1
	v_cvt_pk_bf16_f32 v1, v2, v3
	global_store_dwordx2 v[72:73], v[0:1], off offset:3584
	v_pk_mul_f32 v[4:5], v[74:75], v[64:65] op_sel_hi:[0,1]
	v_pk_mul_f32 v[6:7], v[74:75], v[62:63] op_sel_hi:[0,1]
	v_pk_mul_f32 v[4:5], v[238:239], v[4:5]
	v_pk_mul_f32 v[6:7], v[240:241], v[6:7]
	v_cvt_pk_bf16_f32 v4, v4, v5
	v_cvt_pk_bf16_f32 v5, v6, v7
	global_store_dwordx2 v[72:73], v[4:5], off offset:3616
	v_pk_mul_f32 v[0:1], v[74:75], v[76:77] op_sel_hi:[0,1]
	v_pk_mul_f32 v[2:3], v[74:75], v[66:67] op_sel_hi:[0,1]
	v_pk_mul_f32 v[0:1], v[244:245], v[0:1]
	v_pk_mul_f32 v[2:3], v[246:247], v[2:3]
	v_cvt_pk_bf16_f32 v0, v0, v1
	v_cvt_pk_bf16_f32 v1, v2, v3
	global_store_dwordx2 v[72:73], v[0:1], off offset:3840
	v_pk_mul_f32 v[4:5], v[74:75], v[56:57] op_sel_hi:[0,1]
	v_pk_mul_f32 v[6:7], v[74:75], v[50:51] op_sel_hi:[0,1]
	v_pk_mul_f32 v[4:5], v[248:249], v[4:5]
	v_pk_mul_f32 v[6:7], v[250:251], v[6:7]
	v_cvt_pk_bf16_f32 v4, v4, v5
	v_cvt_pk_bf16_f32 v5, v6, v7
	global_store_dwordx2 v[72:73], v[4:5], off offset:3872
	s_barrier
	s_cbranch_scc0 .LBB0_775
; #define LAS __attribute__((address_space(3)))
; __global__ void __launch_bounds__(NTHR, 2) fwd_megakernel(Args args) {
;     ...
;         for (int su = bid; su < T / 32; su += G) {
;             const int tc0 = (su >> 2) * 128, qi = su & 3, i0 = 32 * qi, J = qi < 2 ? 64 : 128;
;             constexpr int LDB = 136;
;             LAS bf16_t* Bt = (LAS bf16_t*)lds;
;             LAS f32x2* st = (LAS f32x2*)(lds + 2 * 128 * LDB * 2);
;             LAS float* red = (LAS float*)(lds + 2 * 128 * LDB * 2 + 1024);
;             if (tid < J) { const f32x4* p = (const f32x4*)(VSTAT + (size_t)(tc0 + tid) * 32); float s1 = 0.f, s2 = 0.f;
; #pragma unroll
;                 for (int j = 0; j < 8; ++j) { const f32x4 v = p[j]; s1 += v[0] + v[2]; s2 += v[1] + v[3]; }
;                 const float mean = s1 * (1.0f / CCH), var = fmaxf(s2 * (1.0f / CCH) - mean * mean, 0.f); st[tid] = (f32x2){mean, rsqrtf(var + LN_EPS)}; }
.LBB0_659:
	global_load_dwordx4 v[240:243], v[212:213], off
	global_load_dwordx4 v[244:247], v[214:215], off
	s_and_b32 s11, s23, 0xffffff80
	s_and_b32 s44, s58, 3
	v_lshrrev_b32_e32 v218, 4, v221
	v_lshl_or_b32 v218, s44, 5, v218
	v_and_b32_e32 v219, 15, v221
	v_lshlrev_b32_e32 v219, 4, v219
	v_lshl_add_u32 v218, v218, 8, v219
	v_mov_b32_e32 v219, 0
	s_add_u32 s100, s14, 0xbc08000
	s_addc_u32 s101, s15, 0
	v_lshl_add_u64 v[218:219], s[100:101], 0, v[218:219]
	s_mov_b64 s[100:101], 0x8000
	s_cmp_gt_u32 s44, 1
	s_cselect_b64 s[26:27], -1, 0
	s_and_b64 s[4:5], s[26:27], exec
	s_cselect_b32 s4, 0x80, 64
	v_cmp_gt_u32_e32 vcc, s4, v221
	s_and_saveexec_b64 s[4:5], vcc
	s_cbranch_execz .LBB0_661
	v_add_u32_e32 v8, s11, v221
	v_ashrrev_i32_e32 v9, 31, v8
	v_lshlrev_b64 v[8:9], 7, v[8:9]
	v_lshl_add_u64 v[44:45], s[38:39], 0, v[8:9]
	global_load_dwordx4 v[8:11], v[44:45], off
	global_load_dwordx4 v[12:15], v[44:45], off offset:16
	global_load_dwordx4 v[16:19], v[44:45], off offset:32
	global_load_dwordx4 v[20:23], v[44:45], off offset:48
	global_load_dwordx4 v[24:27], v[44:45], off offset:64
	global_load_dwordx4 v[28:31], v[44:45], off offset:80
	global_load_dwordx4 v[40:43], v[44:45], off offset:96
	s_nop 0
	global_load_dwordx4 v[44:47], v[44:45], off offset:112
	s_waitcnt vmcnt(7)
	v_pk_add_f32 v[8:9], v[8:9], v[10:11]
	s_waitcnt vmcnt(6)
	v_pk_add_f32 v[10:11], v[12:13], v[14:15]
	v_pk_add_f32 v[8:9], v[8:9], 0 op_sel_hi:[1,0]
	s_waitcnt vmcnt(5)
	v_pk_add_f32 v[12:13], v[16:17], v[18:19]
	v_pk_add_f32 v[8:9], v[8:9], v[10:11]
	s_waitcnt vmcnt(4)
	v_pk_add_f32 v[14:15], v[20:21], v[22:23]
	v_pk_add_f32 v[8:9], v[8:9], v[12:13]
	s_waitcnt vmcnt(3)
	v_pk_add_f32 v[16:17], v[24:25], v[26:27]
	v_pk_add_f32 v[8:9], v[8:9], v[14:15]
	s_waitcnt vmcnt(2)
	v_pk_add_f32 v[18:19], v[28:29], v[30:31]
	v_pk_add_f32 v[8:9], v[8:9], v[16:17]
	s_waitcnt vmcnt(1)
	v_pk_add_f32 v[20:21], v[40:41], v[42:43]
	v_pk_add_f32 v[8:9], v[8:9], v[18:19]
	s_waitcnt vmcnt(0)
	v_pk_add_f32 v[22:23], v[44:45], v[46:47]
	v_pk_add_f32 v[8:9], v[8:9], v[20:21]
	s_nop 0
	v_pk_add_f32 v[8:9], v[8:9], v[22:23]
	s_nop 0
	v_pk_mul_f32 v[8:9], v[8:9], s[22:23] op_sel_hi:[1,0]
	s_nop 0
	v_fma_f32 v9, -v8, v8, v9
	v_max_f32_e32 v9, 0, v9
	v_add_f32_e32 v9, 0x3727c5ac, v9
	v_mul_f32_e32 v10, 0x4b800000, v9
	v_cmp_gt_f32_e32 vcc, s57, v9
	s_nop 1
	v_cndmask_b32_e32 v9, v9, v10, vcc
	v_rsq_f32_e32 v9, v9
	s_nop 0
	v_mul_f32_e32 v10, 0x45800000, v9
	v_cndmask_b32_e32 v9, v9, v10, vcc
	ds_write_b64 v137, v[8:9]

; #define LAS __attribute__((address_space(3)))
; __device__ __forceinline__ unsigned cvt_pk_bf16(float lo, float hi) { unsigned r; asm volatile("v_cvt_pk_bf16_f32 %0, %1, %2" : "=v"(r) : "v"(lo), "v"(hi)); return r; }
; __device__ __forceinline__ float bf_lo(unsigned u) { return __uint_as_float(u << 16); }
; __device__ __forceinline__ float bf_hi(unsigned u) { return __uint_as_float(u & 0xffff0000u); }
; #define KIN(i) (*(const float* const __attribute__((address_space(4)))*)(kp + kz + 8 * (i)))
; __global__ void __launch_bounds__(NTHR, 2) fwd_megakernel(Args args) {
;     ...
;             const int trow = tc0 + i0 + 16 * mb + fr;
;             const float* lng = KIN(I_SGU_LN_G); const float* lnb = KIN(I_SGU_LN_B); const float* sgb = KIN(I_SGU_B);
;             const int c8 = tid & 15, jb = tid >> 4, nk = J / 32;
;             u32x4 pv[4]; f32x4 pg0, pg1, pb0, pb1; bf16x8 pw[4]; u32x2 pu0, pu1; float pbs;
;     ...
;             f32x4 yv[8][2]; float ss = 0.f;
;             SGU_PREFETCH(0);
;             __syncthreads();
; #pragma unroll
;             for (int h = 0; h < 8; ++h) {
;                 LAS bf16_t* Bc = Bt + (h & 1) * (128 * LDB);
; #pragma unroll
;                 for (int k = 0; k < 4; ++k) if (k < nk) { const int j = jb + 32 * k; const u32x4 v = pv[k]; const f32x2 ms = st[j];
;                     const f32x4 x0 = (f32x4){bf_lo(v.x), bf_hi(v.x), bf_lo(v.y), bf_hi(v.y)}, x1 = (f32x4){bf_lo(v.z), bf_hi(v.z), bf_lo(v.w), bf_hi(v.w)};
;                     const f32x4 y0 = (x0 - ms.x) * ms.y * pg0 + pb0, y1 = (x1 - ms.x) * ms.y * pg1 + pb1;
;                     LAS bf16_t* d = Bc + (c8 * 8) * LDB + (j ^ (8 * c8));
;                     const unsigned p0 = cvt_pk_bf16(y0[0], y0[1]), p1 = cvt_pk_bf16(y0[2], y0[3]), p2 = cvt_pk_bf16(y1[0], y1[1]), p3 = cvt_pk_bf16(y1[2], y1[3]);
;                     d[0 * LDB] = (bf16_t)(p0 & 0xffffu); d[1 * LDB] = (bf16_t)(p0 >> 16); d[2 * LDB] = (bf16_t)(p1 & 0xffffu); d[3 * LDB] = (bf16_t)(p1 >> 16);
;                     d[4 * LDB] = (bf16_t)(p2 & 0xffffu); d[5 * LDB] = (bf16_t)(p2 >> 16); d[6 * LDB] = (bf16_t)(p3 & 0xffffu); d[7 * LDB] = (bf16_t)(p3 >> 16); }
.LBB0_669:
	v_or_b32_e32 v134, s11, v48
	v_ashrrev_i32_e32 v135, 31, v134
	v_lshlrev_b32_e32 v120, 2, v48
	v_add_u32_e32 v223, 0x14600, v120
	v_lshlrev_b64 v[48:49], 11, v[134:135]
	v_lshl_add_u64 v[150:151], v[130:131], 0, v[48:49]
	global_load_dword v136, v120, s[20:21]
	global_load_dwordx2 v[140:141], v[150:151], off
	global_load_dwordx2 v[138:139], v[150:151], off offset:32
	s_waitcnt vmcnt(7)
	v_lshlrev_b32_e32 v238, 4, v221
	v_add_u32_e32 v238, 0x11600, v238
	v_mov_b32_e32 v239, v221
	v_lshlrev_b32_e32 v239, 4, v239
	v_add_u32_e32 v239, 0x13600, v239
	ds_write_b128 v238, v[240:243]
	ds_write_b128 v239, v[244:247]
	s_waitcnt lgkmcnt(0)
	s_barrier
	ds_read_b128 v[16:19], v203 offset:16
	ds_read_b128 v[24:27], v203
	ds_read_b128 v[20:23], v203 offset:4112
	ds_read_b128 v[28:31], v203 offset:4096
	ds_read_b64 v[48:49], v181
	s_waitcnt vmcnt(6)
	v_lshlrev_b32_e32 v50, 16, v44
	v_and_b32_e32 v51, 0xffff0000, v44
	v_lshlrev_b32_e32 v44, 16, v45
	v_and_b32_e32 v45, 0xffff0000, v45
	v_lshlrev_b32_e32 v52, 16, v46
	v_and_b32_e32 v53, 0xffff0000, v46
	v_lshlrev_b32_e32 v54, 16, v47
	v_and_b32_e32 v55, 0xffff0000, v47
	s_waitcnt lgkmcnt(0)
	v_sub_f32_e32 v47, v51, v48
	v_sub_f32_e32 v46, v50, v48
	v_sub_f32_e32 v45, v45, v48
	v_sub_f32_e32 v44, v44, v48
	v_pk_mul_f32 v[46:47], v[48:49], v[46:47] op_sel:[1,0]
	v_pk_mul_f32 v[44:45], v[48:49], v[44:45] op_sel:[1,0]
	s_waitcnt vmcnt(5)
	v_pk_fma_f32 v[46:47], v[24:25], v[46:47], v[28:29]
	v_sub_f32_e32 v51, v55, v48
	v_sub_f32_e32 v50, v54, v48
	v_sub_f32_e32 v53, v53, v48
	v_sub_f32_e32 v52, v52, v48
	v_pk_fma_f32 v[44:45], v[26:27], v[44:45], v[30:31]
	v_pk_mul_f32 v[52:53], v[48:49], v[52:53] op_sel:[1,0]
	v_pk_mul_f32 v[48:49], v[48:49], v[50:51] op_sel:[1,0]
	v_cvt_pk_bf16_f32 v46, v46, v47
	v_pk_fma_f32 v[50:51], v[16:17], v[52:53], v[20:21]
	v_pk_fma_f32 v[48:49], v[18:19], v[48:49], v[22:23]
	v_cvt_pk_bf16_f32 v44, v44, v45
	v_cvt_pk_bf16_f32 v45, v50, v51
	v_lshlrev_b32_e32 v50, 16, v43
	v_cvt_pk_bf16_f32 v47, v48, v49
	ds_write_b16 v186, v46
	ds_write_b16_d16_hi v186, v46 offset:272
	ds_write_b16 v186, v44 offset:544
	ds_write_b16_d16_hi v186, v44 offset:816
	ds_write_b16 v186, v45 offset:1088
	ds_write_b16_d16_hi v186, v45 offset:1360
	ds_write_b16 v186, v47 offset:1632
	ds_write_b16_d16_hi v186, v47 offset:1904
	ds_read_b64 v[44:45], v187
	v_lshlrev_b32_e32 v46, 16, v40
	v_and_b32_e32 v47, 0xffff0000, v40
	v_lshlrev_b32_e32 v40, 16, v41
	v_and_b32_e32 v41, 0xffff0000, v41
	v_lshlrev_b32_e32 v48, 16, v42
	v_and_b32_e32 v49, 0xffff0000, v42
	v_and_b32_e32 v51, 0xffff0000, v43
	s_waitcnt lgkmcnt(0)
	v_sub_f32_e32 v43, v47, v44
	v_sub_f32_e32 v42, v46, v44
	v_sub_f32_e32 v41, v41, v44
	v_sub_f32_e32 v40, v40, v44
	v_pk_mul_f32 v[42:43], v[44:45], v[42:43] op_sel:[1,0]
	v_pk_mul_f32 v[40:41], v[44:45], v[40:41] op_sel:[1,0]
	v_pk_fma_f32 v[42:43], v[24:25], v[42:43], v[28:29]
	v_sub_f32_e32 v47, v51, v44
	v_sub_f32_e32 v46, v50, v44
	v_sub_f32_e32 v49, v49, v44
	v_sub_f32_e32 v48, v48, v44
	v_pk_fma_f32 v[40:41], v[26:27], v[40:41], v[30:31]
	v_pk_mul_f32 v[48:49], v[44:45], v[48:49] op_sel:[1,0]
	v_pk_mul_f32 v[44:45], v[44:45], v[46:47] op_sel:[1,0]
	v_cvt_pk_bf16_f32 v42, v42, v43
	s_and_b64 vcc, exec, s[4:5]
	v_pk_fma_f32 v[44:45], v[18:19], v[44:45], v[22:23]
	v_pk_fma_f32 v[46:47], v[16:17], v[48:49], v[20:21]
	v_cvt_pk_bf16_f32 v40, v40, v41
	s_nop 0
	v_cvt_pk_bf16_f32 v41, v46, v47
	v_cvt_pk_bf16_f32 v43, v44, v45
	ds_write_b16 v188, v42
	ds_write_b16_d16_hi v188, v42 offset:272
	ds_write_b16 v188, v40 offset:544
	ds_write_b16_d16_hi v188, v40 offset:816
	ds_write_b16 v188, v41 offset:1088
	ds_write_b16_d16_hi v188, v41 offset:1360
	ds_write_b16 v188, v43 offset:1632
	ds_write_b16_d16_hi v188, v43 offset:1904
	s_cbranch_vccnz .LBB0_671
	ds_read_b64 v[40:41], v189
	v_lshlrev_b32_e32 v44, 16, v0
	v_and_b32_e32 v45, 0xffff0000, v0
	v_lshlrev_b32_e32 v42, 16, v1
	v_and_b32_e32 v43, 0xffff0000, v1
	v_lshlrev_b32_e32 v48, 16, v2
	v_and_b32_e32 v49, 0xffff0000, v2
	v_lshlrev_b32_e32 v46, 16, v3
	v_and_b32_e32 v47, 0xffff0000, v3
	s_waitcnt lgkmcnt(0)
	v_sub_f32_e32 v45, v45, v40
	v_sub_f32_e32 v44, v44, v40
	v_sub_f32_e32 v43, v43, v40
	v_sub_f32_e32 v42, v42, v40
	v_pk_mul_f32 v[44:45], v[40:41], v[44:45] op_sel:[1,0]
	v_sub_f32_e32 v47, v47, v40
	v_sub_f32_e32 v46, v46, v40
	v_sub_f32_e32 v49, v49, v40
	v_sub_f32_e32 v48, v48, v40
	v_pk_mul_f32 v[42:43], v[40:41], v[42:43] op_sel:[1,0]
	v_pk_fma_f32 v[44:45], v[24:25], v[44:45], v[28:29]
	v_pk_mul_f32 v[48:49], v[40:41], v[48:49] op_sel:[1,0]
	v_pk_mul_f32 v[40:41], v[40:41], v[46:47] op_sel:[1,0]
	v_pk_fma_f32 v[42:43], v[26:27], v[42:43], v[30:31]
	v_pk_fma_f32 v[40:41], v[18:19], v[40:41], v[22:23]
	v_cvt_pk_bf16_f32 v44, v44, v45
	v_pk_fma_f32 v[46:47], v[16:17], v[48:49], v[20:21]
	v_cvt_pk_bf16_f32 v42, v42, v43
	v_and_b32_e32 v45, 0xffff0000, v4
	v_cvt_pk_bf16_f32 v43, v46, v47
	v_cvt_pk_bf16_f32 v40, v40, v41
	ds_write_b16 v190, v44
	ds_write_b16_d16_hi v190, v44 offset:272
	ds_write_b16 v190, v42 offset:544
	ds_write_b16_d16_hi v190, v42 offset:816
	ds_write_b16 v190, v43 offset:1088
	ds_write_b16_d16_hi v190, v43 offset:1360
	ds_write_b16 v190, v40 offset:1632
	ds_write_b16_d16_hi v190, v40 offset:1904
	ds_read_b64 v[40:41], v191
	v_lshlrev_b32_e32 v42, 16, v5
	v_and_b32_e32 v43, 0xffff0000, v5
	v_lshlrev_b32_e32 v44, 16, v4
	v_lshlrev_b32_e32 v46, 16, v6
	s_waitcnt lgkmcnt(0)
	v_sub_f32_e32 v43, v43, v40
	v_sub_f32_e32 v42, v42, v40
	v_and_b32_e32 v47, 0xffff0000, v6
	v_sub_f32_e32 v45, v45, v40
	v_sub_f32_e32 v44, v44, v40
	v_pk_mul_f32 v[42:43], v[40:41], v[42:43] op_sel:[1,0]
	v_lshlrev_b32_e32 v48, 16, v7
	v_and_b32_e32 v49, 0xffff0000, v7
	v_pk_mul_f32 v[44:45], v[40:41], v[44:45] op_sel:[1,0]
	v_pk_fma_f32 v[26:27], v[26:27], v[42:43], v[30:31]
	v_sub_f32_e32 v31, v47, v40
	v_sub_f32_e32 v30, v46, v40
	v_pk_fma_f32 v[24:25], v[24:25], v[44:45], v[28:29]
	v_sub_f32_e32 v29, v49, v40
	v_sub_f32_e32 v28, v48, v40
	v_pk_mul_f32 v[30:31], v[40:41], v[30:31] op_sel:[1,0]
	v_pk_mul_f32 v[28:29], v[40:41], v[28:29] op_sel:[1,0]
	v_pk_fma_f32 v[16:17], v[16:17], v[30:31], v[20:21]
	v_cvt_pk_bf16_f32 v20, v24, v25
	v_pk_fma_f32 v[18:19], v[18:19], v[28:29], v[22:23]
	v_cvt_pk_bf16_f32 v21, v26, v27
	v_cvt_pk_bf16_f32 v16, v16, v17
	s_nop 0
	v_cvt_pk_bf16_f32 v17, v18, v19
	ds_write_b16 v192, v20
	ds_write_b16_d16_hi v192, v20 offset:272
	ds_write_b16 v192, v21 offset:544
	ds_write_b16_d16_hi v192, v21 offset:816
	ds_write_b16 v192, v16 offset:1088
	ds_write_b16_d16_hi v192, v16 offset:1360
	ds_write_b16 v192, v17 offset:1632
	ds_write_b16_d16_hi v192, v17 offset:1904

; #define LAS __attribute__((address_space(3)))
; __global__ void __launch_bounds__(NTHR, 2) fwd_megakernel(Args args) {
;     ...
;                 f32x4 a0 = (f32x4){0.f, 0.f, 0.f, 0.f}, a1 = a0;
; #pragma unroll
;                 for (int ks = 0; ks < 4; ++ks) if (ks < nk) {
;                     const int r0 = 16 * (2 * nq) + fr, r1 = r0 + 16, q = ks * 4 + fq;
;                     const bf16x8 x0 = *(const LAS bf16x8*)(Bc + r0 * LDB + ((q ^ ((r0 >> 3) & 15)) * 8)), x1 = *(const LAS bf16x8*)(Bc + r1 * LDB + ((q ^ ((r1 >> 3) & 15)) * 8));
;                     a0 = __builtin_amdgcn_mfma_f32_16x16x32_bf16(x0, cw[ks], a0, 0, 0, 0); a1 = __builtin_amdgcn_mfma_f32_16x16x32_bf16(x1, cw[ks], a1, 0, 0, 0);
;                 }
.LBB0_675:
	s_nop 0
	ds_read_b128 v[40:43], v203 offset:528
	ds_read_b128 v[48:51], v203 offset:512
	ds_read_b128 v[44:47], v203 offset:4624
	ds_read_b128 v[52:55], v203 offset:4608
	v_add_co_u32_e32 v16, vcc, 0x8000, v148
	s_waitcnt vmcnt(5)
	v_mov_b64_e32 v[28:29], v[36:37]
	v_addc_co_u32_e32 v17, vcc, 0, v149, vcc
	global_load_dwordx4 v[224:227], v[218:219], off
	v_lshl_add_u64 v[218:219], v[218:219], 0, s[100:101]
	s_nop 0
	s_nop 0
	s_and_b64 vcc, exec, s[4:5]
	v_mov_b64_e32 v[30:31], v[38:39]
	s_cbranch_vccnz .LBB0_677
	v_add_co_u32_e32 v24, vcc, 0x8000, v148
	s_nop 1
	v_addc_co_u32_e32 v25, vcc, 0, v149, vcc
	s_nop 0
.LBB0_677:
	v_mov_b64_e32 v[24:25], v[32:33]
	s_and_b64 vcc, exec, s[4:5]
	v_mov_b64_e32 v[26:27], v[34:35]
	s_cbranch_vccnz .LBB0_679
	v_add_co_u32_e32 v24, vcc, 0x8000, v148
	s_nop 1
	v_addc_co_u32_e32 v25, vcc, 0, v149, vcc
	s_nop 0
.LBB0_679:
	v_lshl_add_u64 v[160:161], s[20:21], 0, v[120:121]
	ds_read_b128 v[64:67], v193
	ds_read_b128 v[68:71], v194
	ds_read_b128 v[72:75], v195
	ds_read_b128 v[76:79], v196
	s_nop 0
	global_load_dwordx2 v[144:145], v[150:151], off offset:256
	global_load_dwordx2 v[142:143], v[150:151], off offset:288
	s_waitcnt lgkmcnt(3)
	v_mfma_f32_16x16x32_bf16 v[64:67], v[64:67], v[12:15], 0
	s_and_b64 vcc, exec, s[4:5]
	s_waitcnt lgkmcnt(2)
	v_mfma_f32_16x16x32_bf16 v[68:71], v[68:71], v[12:15], 0
	s_waitcnt lgkmcnt(1)
	v_mfma_f32_16x16x32_bf16 v[12:15], v[72:75], v[8:11], v[64:67]
	s_waitcnt lgkmcnt(0)
	v_mfma_f32_16x16x32_bf16 v[8:11], v[76:79], v[8:11], v[68:71]
	s_cbranch_vccnz .LBB0_681
	ds_read_b128 v[64:67], v197
	s_nop 1
	ds_read_b128 v[68:71], v198
	s_waitcnt lgkmcnt(1)
	v_mfma_f32_16x16x32_bf16 v[12:15], v[64:67], v[36:39], v[12:15]
	s_waitcnt lgkmcnt(0)
	v_mfma_f32_16x16x32_bf16 v[8:11], v[68:71], v[36:39], v[8:11]

; #define LAS __attribute__((address_space(3)))
; __device__ __forceinline__ unsigned cvt_pk_bf16(float lo, float hi) { unsigned r; asm volatile("v_cvt_pk_bf16_f32 %0, %1, %2" : "=v"(r) : "v"(lo), "v"(hi)); return r; }
; __device__ __forceinline__ float bf_lo(unsigned u) { return __uint_as_float(u << 16); }
; __device__ __forceinline__ float bf_hi(unsigned u) { return __uint_as_float(u & 0xffff0000u); }
; __global__ void __launch_bounds__(NTHR, 2) fwd_megakernel(Args args) {
;     ...
;                 for (int k = 0; k < 4; ++k) if (k < nk) { const int j = jb + 32 * k; const u32x4 v = pv[k]; const f32x2 ms = st[j];
;                     const f32x4 x0 = (f32x4){bf_lo(v.x), bf_hi(v.x), bf_lo(v.y), bf_hi(v.y)}, x1 = (f32x4){bf_lo(v.z), bf_hi(v.z), bf_lo(v.w), bf_hi(v.w)};
;                     const f32x4 y0 = (x0 - ms.x) * ms.y * pg0 + pb0, y1 = (x1 - ms.x) * ms.y * pg1 + pb1;
;                     LAS bf16_t* d = Bc + (c8 * 8) * LDB + (j ^ (8 * c8));
;                     const unsigned p0 = cvt_pk_bf16(y0[0], y0[1]), p1 = cvt_pk_bf16(y0[2], y0[3]), p2 = cvt_pk_bf16(y1[0], y1[1]), p3 = cvt_pk_bf16(y1[2], y1[3]);
;                     d[0 * LDB] = (bf16_t)(p0 & 0xffffu); d[1 * LDB] = (bf16_t)(p0 >> 16); d[2 * LDB] = (bf16_t)(p1 & 0xffffu); d[3 * LDB] = (bf16_t)(p1 >> 16);
;                     d[4 * LDB] = (bf16_t)(p2 & 0xffffu); d[5 * LDB] = (bf16_t)(p2 >> 16); d[6 * LDB] = (bf16_t)(p3 & 0xffffu); d[7 * LDB] = (bf16_t)(p3 >> 16); }
;                 bf16x8 cw[4];
; #pragma unroll
;                 for (int ks = 0; ks < 4; ++ks) cw[ks] = pw[ks];
;                 const u32x2 u0 = pu0, u1 = pu1; const float bs = pbs;
;                 __syncthreads();
;                 if (h + 1 < 8) SGU_PREFETCH(h + 1);
.LBB0_683:
	ds_read_b64 v[32:33], v181
	s_waitcnt vmcnt(4)
	v_lshlrev_b32_e32 v36, 16, v60
	v_and_b32_e32 v37, 0xffff0000, v60
	v_lshlrev_b32_e32 v34, 16, v61
	v_and_b32_e32 v35, 0xffff0000, v61
	v_lshlrev_b32_e32 v60, 16, v62
	v_and_b32_e32 v61, 0xffff0000, v62
	v_lshlrev_b32_e32 v38, 16, v63
	v_and_b32_e32 v39, 0xffff0000, v63
	s_waitcnt lgkmcnt(0)
	v_sub_f32_e32 v37, v37, v32
	v_sub_f32_e32 v36, v36, v32
	v_sub_f32_e32 v35, v35, v32
	v_sub_f32_e32 v34, v34, v32
	v_pk_mul_f32 v[36:37], v[32:33], v[36:37] op_sel:[1,0]
	v_sub_f32_e32 v39, v39, v32
	v_sub_f32_e32 v38, v38, v32
	v_sub_f32_e32 v61, v61, v32
	v_sub_f32_e32 v60, v60, v32
	v_pk_mul_f32 v[34:35], v[32:33], v[34:35] op_sel:[1,0]
	s_waitcnt vmcnt(3)
	v_pk_fma_f32 v[36:37], v[48:49], v[36:37], v[52:53]
	v_pk_mul_f32 v[60:61], v[32:33], v[60:61] op_sel:[1,0]
	v_pk_mul_f32 v[32:33], v[32:33], v[38:39] op_sel:[1,0]
	v_pk_fma_f32 v[34:35], v[50:51], v[34:35], v[54:55]
	v_pk_fma_f32 v[32:33], v[42:43], v[32:33], v[46:47]
	v_cvt_pk_bf16_f32 v36, v36, v37
	v_pk_fma_f32 v[38:39], v[40:41], v[60:61], v[44:45]
	v_cvt_pk_bf16_f32 v34, v34, v35
	v_and_b32_e32 v37, 0xffff0000, v56
	v_cvt_pk_bf16_f32 v35, v38, v39
	v_cvt_pk_bf16_f32 v32, v32, v33
	ds_write_b16 v186, v36 offset:34816
	ds_write_b16_d16_hi v186, v36 offset:35088
	ds_write_b16 v186, v34 offset:35360
	ds_write_b16_d16_hi v186, v34 offset:35632
	ds_write_b16 v186, v35 offset:35904
	ds_write_b16_d16_hi v186, v35 offset:36176
	ds_write_b16 v186, v32 offset:36448
	ds_write_b16_d16_hi v186, v32 offset:36720
	ds_read_b64 v[32:33], v187
	v_lshlrev_b32_e32 v36, 16, v56
	v_lshlrev_b32_e32 v34, 16, v57
	v_and_b32_e32 v35, 0xffff0000, v57
	v_lshlrev_b32_e32 v56, 16, v58
	v_and_b32_e32 v57, 0xffff0000, v58
	v_lshlrev_b32_e32 v38, 16, v59
	v_and_b32_e32 v39, 0xffff0000, v59
	s_waitcnt lgkmcnt(0)
	v_sub_f32_e32 v37, v37, v32
	v_sub_f32_e32 v36, v36, v32
	v_sub_f32_e32 v35, v35, v32
	v_sub_f32_e32 v34, v34, v32
	v_pk_mul_f32 v[36:37], v[32:33], v[36:37] op_sel:[1,0]
	v_sub_f32_e32 v39, v39, v32
	v_sub_f32_e32 v38, v38, v32
	v_sub_f32_e32 v57, v57, v32
	v_sub_f32_e32 v56, v56, v32
	v_pk_mul_f32 v[34:35], v[32:33], v[34:35] op_sel:[1,0]
	v_pk_fma_f32 v[36:37], v[48:49], v[36:37], v[52:53]
	v_pk_mul_f32 v[56:57], v[32:33], v[56:57] op_sel:[1,0]
	v_pk_mul_f32 v[32:33], v[32:33], v[38:39] op_sel:[1,0]
	v_pk_fma_f32 v[34:35], v[50:51], v[34:35], v[54:55]
	v_pk_fma_f32 v[32:33], v[42:43], v[32:33], v[46:47]
	v_cvt_pk_bf16_f32 v36, v36, v37
	s_and_b64 vcc, exec, s[4:5]
	v_pk_fma_f32 v[38:39], v[40:41], v[56:57], v[44:45]
	v_cvt_pk_bf16_f32 v34, v34, v35
	s_nop 0
	v_cvt_pk_bf16_f32 v35, v38, v39
	v_cvt_pk_bf16_f32 v32, v32, v33
	ds_write_b16 v188, v36 offset:34816
	ds_write_b16_d16_hi v188, v36 offset:35088
	ds_write_b16 v188, v34 offset:35360
	ds_write_b16_d16_hi v188, v34 offset:35632
	ds_write_b16 v188, v35 offset:35904
	ds_write_b16_d16_hi v188, v35 offset:36176
	ds_write_b16 v188, v32 offset:36448
	ds_write_b16_d16_hi v188, v32 offset:36720
	s_cbranch_vccnz .LBB0_685
	ds_read_b64 v[32:33], v189
	v_lshlrev_b32_e32 v36, 16, v0
	v_and_b32_e32 v37, 0xffff0000, v0
	v_lshlrev_b32_e32 v34, 16, v1
	v_and_b32_e32 v35, 0xffff0000, v1
	v_lshlrev_b32_e32 v56, 16, v2
	v_and_b32_e32 v57, 0xffff0000, v2
	v_lshlrev_b32_e32 v38, 16, v3
	v_and_b32_e32 v39, 0xffff0000, v3
	s_waitcnt lgkmcnt(0)
	v_sub_f32_e32 v37, v37, v32
	v_sub_f32_e32 v36, v36, v32
	v_sub_f32_e32 v35, v35, v32
	v_sub_f32_e32 v34, v34, v32
	v_pk_mul_f32 v[36:37], v[32:33], v[36:37] op_sel:[1,0]
	v_sub_f32_e32 v39, v39, v32
	v_sub_f32_e32 v38, v38, v32
	v_sub_f32_e32 v57, v57, v32
	v_sub_f32_e32 v56, v56, v32
	v_pk_mul_f32 v[34:35], v[32:33], v[34:35] op_sel:[1,0]
	v_pk_fma_f32 v[36:37], v[48:49], v[36:37], v[52:53]
	v_pk_mul_f32 v[56:57], v[32:33], v[56:57] op_sel:[1,0]
	v_pk_mul_f32 v[32:33], v[32:33], v[38:39] op_sel:[1,0]
	v_pk_fma_f32 v[34:35], v[50:51], v[34:35], v[54:55]
	v_pk_fma_f32 v[32:33], v[42:43], v[32:33], v[46:47]
	v_cvt_pk_bf16_f32 v36, v36, v37
	v_pk_fma_f32 v[38:39], v[40:41], v[56:57], v[44:45]
	v_cvt_pk_bf16_f32 v34, v34, v35
	v_and_b32_e32 v37, 0xffff0000, v4
	v_cvt_pk_bf16_f32 v35, v38, v39
	v_cvt_pk_bf16_f32 v32, v32, v33
	ds_write_b16 v190, v36 offset:34816
	ds_write_b16_d16_hi v190, v36 offset:35088
	ds_write_b16 v190, v34 offset:35360
	ds_write_b16_d16_hi v190, v34 offset:35632
	ds_write_b16 v190, v35 offset:35904
	ds_write_b16_d16_hi v190, v35 offset:36176
	ds_write_b16 v190, v32 offset:36448
	ds_write_b16_d16_hi v190, v32 offset:36720
	ds_read_b64 v[32:33], v191
	v_lshlrev_b32_e32 v36, 16, v4
	v_lshlrev_b32_e32 v34, 16, v5
	v_and_b32_e32 v35, 0xffff0000, v5
	v_lshlrev_b32_e32 v56, 16, v6
	s_waitcnt lgkmcnt(0)
	v_sub_f32_e32 v37, v37, v32
	v_sub_f32_e32 v36, v36, v32
	v_and_b32_e32 v57, 0xffff0000, v6
	v_lshlrev_b32_e32 v38, 16, v7
	v_and_b32_e32 v39, 0xffff0000, v7
	v_pk_mul_f32 v[36:37], v[32:33], v[36:37] op_sel:[1,0]
	v_sub_f32_e32 v35, v35, v32
	v_sub_f32_e32 v34, v34, v32
	v_pk_fma_f32 v[36:37], v[48:49], v[36:37], v[52:53]
	v_sub_f32_e32 v39, v39, v32
	v_sub_f32_e32 v38, v38, v32
	v_sub_f32_e32 v49, v57, v32
	v_sub_f32_e32 v48, v56, v32
	v_pk_mul_f32 v[34:35], v[32:33], v[34:35] op_sel:[1,0]
	v_pk_mul_f32 v[48:49], v[32:33], v[48:49] op_sel:[1,0]
	v_pk_mul_f32 v[32:33], v[32:33], v[38:39] op_sel:[1,0]
	v_pk_fma_f32 v[34:35], v[50:51], v[34:35], v[54:55]
	v_pk_fma_f32 v[32:33], v[42:43], v[32:33], v[46:47]
	v_cvt_pk_bf16_f32 v36, v36, v37
	v_pk_fma_f32 v[38:39], v[40:41], v[48:49], v[44:45]
	v_cvt_pk_bf16_f32 v34, v34, v35
	s_nop 0
	v_cvt_pk_bf16_f32 v35, v38, v39
	v_cvt_pk_bf16_f32 v32, v32, v33
	ds_write_b16 v192, v36 offset:34816
	ds_write_b16_d16_hi v192, v36 offset:35088
	ds_write_b16 v192, v34 offset:35360
	ds_write_b16_d16_hi v192, v34 offset:35632
	ds_write_b16 v192, v35 offset:35904
	ds_write_b16_d16_hi v192, v35 offset:36176
	ds_write_b16 v192, v32 offset:36448
	ds_write_b16_d16_hi v192, v32 offset:36720
.LBB0_685:
	s_waitcnt vmcnt(2)
	ds_write_b128 v228, v[224:227] offset:8704
	s_waitcnt lgkmcnt(0)
	s_barrier
	ds_read_b128 v[20:23], v229 offset:8704
	ds_read_b128 v[16:19], v229 offset:8768
	ds_read_b128 v[28:31], v229 offset:8832
	ds_read_b128 v[24:27], v229 offset:8896
	ds_read_b32 v120, v223 offset:512
	global_load_dwordx4 v[68:71], v[112:113], off offset:512
	global_load_dwordx4 v[64:67], v[114:115], off offset:512
	s_and_b64 vcc, exec, s[4:5]
	s_cbranch_vccnz .LBB0_687
	v_lshlrev_b64 v[0:1], 11, v[152:153]
	v_lshl_add_u64 v[0:1], v[122:123], 0, v[0:1]
	global_load_dwordx4 v[0:3], v[0:1], off offset:512

; #define LAS __attribute__((address_space(3)))
; __global__ void __launch_bounds__(NTHR, 2) fwd_megakernel(Args args) {
;     ...
;                 f32x4 a0 = (f32x4){0.f, 0.f, 0.f, 0.f}, a1 = a0;
; #pragma unroll
;                 for (int ks = 0; ks < 4; ++ks) if (ks < nk) {
;                     const int r0 = 16 * (2 * nq) + fr, r1 = r0 + 16, q = ks * 4 + fq;
;                     const bf16x8 x0 = *(const LAS bf16x8*)(Bc + r0 * LDB + ((q ^ ((r0 >> 3) & 15)) * 8)), x1 = *(const LAS bf16x8*)(Bc + r1 * LDB + ((q ^ ((r1 >> 3) & 15)) * 8));
;                     a0 = __builtin_amdgcn_mfma_f32_16x16x32_bf16(x0, cw[ks], a0, 0, 0, 0); a1 = __builtin_amdgcn_mfma_f32_16x16x32_bf16(x1, cw[ks], a1, 0, 0, 0);
;                 }
.LBB0_689:
	s_nop 0
	ds_read_b128 v[36:39], v203 offset:1040
	ds_read_b128 v[52:55], v203 offset:1024
	ds_read_b128 v[48:51], v203 offset:5136
	ds_read_b128 v[60:63], v203 offset:5120
	v_add_co_u32_e32 v32, vcc, 0x10000, v148
	s_waitcnt vmcnt(5)
	v_mov_b64_e32 v[46:47], v[30:31]
	v_addc_co_u32_e32 v33, vcc, 0, v149, vcc
	global_load_dwordx4 v[224:227], v[218:219], off
	v_lshl_add_u64 v[218:219], v[218:219], 0, s[100:101]
	s_nop 0
	s_and_b64 vcc, exec, s[4:5]
	v_mov_b64_e32 v[44:45], v[28:29]
	s_cbranch_vccnz .LBB0_691
	v_add_co_u32_e32 v32, vcc, 0x10000, v148
	s_nop 1
	v_addc_co_u32_e32 v33, vcc, 0, v149, vcc
	s_nop 0
.LBB0_691:
	v_mov_b64_e32 v[34:35], v[26:27]
	s_and_b64 vcc, exec, s[4:5]
	v_mov_b64_e32 v[32:33], v[24:25]
	s_cbranch_vccnz .LBB0_693
	v_add_co_u32_e32 v32, vcc, 0x10000, v148
	s_nop 1
	v_addc_co_u32_e32 v33, vcc, 0, v149, vcc
	s_nop 0
.LBB0_693:
	ds_read_b128 v[72:75], v193 offset:34816
	ds_read_b128 v[76:79], v194 offset:34816
	s_nop 0
	s_and_b64 vcc, exec, s[4:5]
	s_waitcnt lgkmcnt(1)
	v_mfma_f32_16x16x32_bf16 v[72:75], v[72:75], v[20:23], 0
	ds_read_b128 v[80:83], v196 offset:34816
	s_waitcnt lgkmcnt(1)
	v_mfma_f32_16x16x32_bf16 v[76:79], v[76:79], v[20:23], 0
	ds_read_b128 v[20:23], v195 offset:34816
	global_load_dwordx2 v[158:159], v[150:151], off offset:512
	global_load_dwordx2 v[156:157], v[150:151], off offset:544
	s_waitcnt lgkmcnt(0)
	v_mfma_f32_16x16x32_bf16 v[20:23], v[20:23], v[16:19], v[72:75]
	v_mfma_f32_16x16x32_bf16 v[16:19], v[80:83], v[16:19], v[76:79]
	s_cbranch_vccnz .LBB0_695
	s_nop 0
	ds_read_b128 v[72:75], v197 offset:34816
	ds_read_b128 v[76:79], v198 offset:34816
	s_waitcnt lgkmcnt(1)
	v_mfma_f32_16x16x32_bf16 v[20:23], v[72:75], v[28:31], v[20:23]
	s_waitcnt lgkmcnt(0)
	v_mfma_f32_16x16x32_bf16 v[16:19], v[76:79], v[28:31], v[16:19]

; #define LAS __attribute__((address_space(3)))
; __device__ __forceinline__ unsigned cvt_pk_bf16(float lo, float hi) { unsigned r; asm volatile("v_cvt_pk_bf16_f32 %0, %1, %2" : "=v"(r) : "v"(lo), "v"(hi)); return r; }
; __device__ __forceinline__ float bf_lo(unsigned u) { return __uint_as_float(u << 16); }
; __device__ __forceinline__ float bf_hi(unsigned u) { return __uint_as_float(u & 0xffff0000u); }
; __global__ void __launch_bounds__(NTHR, 2) fwd_megakernel(Args args) {
;     ...
;                 for (int k = 0; k < 4; ++k) if (k < nk) { const int j = jb + 32 * k; const u32x4 v = pv[k]; const f32x2 ms = st[j];
;                     const f32x4 x0 = (f32x4){bf_lo(v.x), bf_hi(v.x), bf_lo(v.y), bf_hi(v.y)}, x1 = (f32x4){bf_lo(v.z), bf_hi(v.z), bf_lo(v.w), bf_hi(v.w)};
;                     const f32x4 y0 = (x0 - ms.x) * ms.y * pg0 + pb0, y1 = (x1 - ms.x) * ms.y * pg1 + pb1;
;                     LAS bf16_t* d = Bc + (c8 * 8) * LDB + (j ^ (8 * c8));
;                     const unsigned p0 = cvt_pk_bf16(y0[0], y0[1]), p1 = cvt_pk_bf16(y0[2], y0[3]), p2 = cvt_pk_bf16(y1[0], y1[1]), p3 = cvt_pk_bf16(y1[2], y1[3]);
;                     d[0 * LDB] = (bf16_t)(p0 & 0xffffu); d[1 * LDB] = (bf16_t)(p0 >> 16); d[2 * LDB] = (bf16_t)(p1 & 0xffffu); d[3 * LDB] = (bf16_t)(p1 >> 16);
;                     d[4 * LDB] = (bf16_t)(p2 & 0xffffu); d[5 * LDB] = (bf16_t)(p2 >> 16); d[6 * LDB] = (bf16_t)(p3 & 0xffffu); d[7 * LDB] = (bf16_t)(p3 >> 16); }
;                 bf16x8 cw[4];
; #pragma unroll
;                 for (int ks = 0; ks < 4; ++ks) cw[ks] = pw[ks];
;                 const u32x2 u0 = pu0, u1 = pu1; const float bs = pbs;
;                 __syncthreads();
;                 if (h + 1 < 8) SGU_PREFETCH(h + 1);
.LBB0_697:
	ds_read_b64 v[24:25], v181
	s_waitcnt vmcnt(4)
	v_lshlrev_b32_e32 v28, 16, v68
	v_and_b32_e32 v29, 0xffff0000, v68
	v_lshlrev_b32_e32 v26, 16, v69
	v_and_b32_e32 v27, 0xffff0000, v69
	v_lshlrev_b32_e32 v68, 16, v70
	v_and_b32_e32 v69, 0xffff0000, v70
	v_lshlrev_b32_e32 v30, 16, v71
	v_and_b32_e32 v31, 0xffff0000, v71
	s_waitcnt lgkmcnt(0)
	v_sub_f32_e32 v29, v29, v24
	v_sub_f32_e32 v28, v28, v24
	v_sub_f32_e32 v27, v27, v24
	v_sub_f32_e32 v26, v26, v24
	v_pk_mul_f32 v[28:29], v[24:25], v[28:29] op_sel:[1,0]
	v_sub_f32_e32 v31, v31, v24
	v_sub_f32_e32 v30, v30, v24
	v_sub_f32_e32 v69, v69, v24
	v_sub_f32_e32 v68, v68, v24
	v_pk_mul_f32 v[26:27], v[24:25], v[26:27] op_sel:[1,0]
	s_waitcnt vmcnt(3)
	v_pk_fma_f32 v[28:29], v[52:53], v[28:29], v[60:61]
	v_pk_mul_f32 v[68:69], v[24:25], v[68:69] op_sel:[1,0]
	v_pk_mul_f32 v[24:25], v[24:25], v[30:31] op_sel:[1,0]
	v_pk_fma_f32 v[26:27], v[54:55], v[26:27], v[62:63]
	v_pk_fma_f32 v[24:25], v[38:39], v[24:25], v[50:51]
	v_cvt_pk_bf16_f32 v28, v28, v29
	v_pk_fma_f32 v[30:31], v[36:37], v[68:69], v[48:49]
	v_cvt_pk_bf16_f32 v26, v26, v27
	v_and_b32_e32 v29, 0xffff0000, v64
	v_cvt_pk_bf16_f32 v27, v30, v31
	v_cvt_pk_bf16_f32 v24, v24, v25
	ds_write_b16 v186, v28
	ds_write_b16_d16_hi v186, v28 offset:272
	ds_write_b16 v186, v26 offset:544
	ds_write_b16_d16_hi v186, v26 offset:816
	ds_write_b16 v186, v27 offset:1088
	ds_write_b16_d16_hi v186, v27 offset:1360
	ds_write_b16 v186, v24 offset:1632
	ds_write_b16_d16_hi v186, v24 offset:1904
	ds_read_b64 v[24:25], v187
	v_lshlrev_b32_e32 v28, 16, v64
	v_lshlrev_b32_e32 v26, 16, v65
	v_and_b32_e32 v27, 0xffff0000, v65
	v_lshlrev_b32_e32 v64, 16, v66
	v_and_b32_e32 v65, 0xffff0000, v66
	v_lshlrev_b32_e32 v30, 16, v67
	v_and_b32_e32 v31, 0xffff0000, v67
	s_waitcnt lgkmcnt(0)
	v_sub_f32_e32 v29, v29, v24
	v_sub_f32_e32 v28, v28, v24
	v_sub_f32_e32 v27, v27, v24
	v_sub_f32_e32 v26, v26, v24
	v_pk_mul_f32 v[28:29], v[24:25], v[28:29] op_sel:[1,0]
	v_sub_f32_e32 v31, v31, v24
	v_sub_f32_e32 v30, v30, v24
	v_sub_f32_e32 v65, v65, v24
	v_sub_f32_e32 v64, v64, v24
	v_pk_mul_f32 v[26:27], v[24:25], v[26:27] op_sel:[1,0]
	v_pk_fma_f32 v[28:29], v[52:53], v[28:29], v[60:61]
	v_pk_mul_f32 v[64:65], v[24:25], v[64:65] op_sel:[1,0]
	v_pk_mul_f32 v[24:25], v[24:25], v[30:31] op_sel:[1,0]
	v_pk_fma_f32 v[26:27], v[54:55], v[26:27], v[62:63]
	v_pk_fma_f32 v[24:25], v[38:39], v[24:25], v[50:51]
	v_cvt_pk_bf16_f32 v28, v28, v29
	s_and_b64 vcc, exec, s[4:5]
	v_pk_fma_f32 v[30:31], v[36:37], v[64:65], v[48:49]
	v_cvt_pk_bf16_f32 v26, v26, v27
	s_nop 0
	v_cvt_pk_bf16_f32 v27, v30, v31
	v_cvt_pk_bf16_f32 v24, v24, v25
	ds_write_b16 v188, v28
	ds_write_b16_d16_hi v188, v28 offset:272
	ds_write_b16 v188, v26 offset:544
	ds_write_b16_d16_hi v188, v26 offset:816
	ds_write_b16 v188, v27 offset:1088
	ds_write_b16_d16_hi v188, v27 offset:1360
	ds_write_b16 v188, v24 offset:1632
	ds_write_b16_d16_hi v188, v24 offset:1904
	s_cbranch_vccnz .LBB0_699
	ds_read_b64 v[24:25], v189
	v_lshlrev_b32_e32 v28, 16, v0
	v_and_b32_e32 v29, 0xffff0000, v0
	v_lshlrev_b32_e32 v26, 16, v1
	v_and_b32_e32 v27, 0xffff0000, v1
	v_lshlrev_b32_e32 v64, 16, v2
	v_and_b32_e32 v65, 0xffff0000, v2
	v_lshlrev_b32_e32 v30, 16, v3
	v_and_b32_e32 v31, 0xffff0000, v3
	s_waitcnt lgkmcnt(0)
	v_sub_f32_e32 v29, v29, v24
	v_sub_f32_e32 v28, v28, v24
	v_sub_f32_e32 v27, v27, v24
	v_sub_f32_e32 v26, v26, v24
	v_pk_mul_f32 v[28:29], v[24:25], v[28:29] op_sel:[1,0]
	v_sub_f32_e32 v31, v31, v24
	v_sub_f32_e32 v30, v30, v24
	v_sub_f32_e32 v65, v65, v24
	v_sub_f32_e32 v64, v64, v24
	v_pk_mul_f32 v[26:27], v[24:25], v[26:27] op_sel:[1,0]
	v_pk_fma_f32 v[28:29], v[52:53], v[28:29], v[60:61]
	v_pk_mul_f32 v[64:65], v[24:25], v[64:65] op_sel:[1,0]
	v_pk_mul_f32 v[24:25], v[24:25], v[30:31] op_sel:[1,0]
	v_pk_fma_f32 v[26:27], v[54:55], v[26:27], v[62:63]
	v_pk_fma_f32 v[24:25], v[38:39], v[24:25], v[50:51]
	v_cvt_pk_bf16_f32 v28, v28, v29
	v_pk_fma_f32 v[30:31], v[36:37], v[64:65], v[48:49]
	v_cvt_pk_bf16_f32 v26, v26, v27
	v_and_b32_e32 v29, 0xffff0000, v4
	v_cvt_pk_bf16_f32 v27, v30, v31
	v_cvt_pk_bf16_f32 v24, v24, v25
	ds_write_b16 v190, v28
	ds_write_b16_d16_hi v190, v28 offset:272
	ds_write_b16 v190, v26 offset:544
	ds_write_b16_d16_hi v190, v26 offset:816
	ds_write_b16 v190, v27 offset:1088
	ds_write_b16_d16_hi v190, v27 offset:1360
	ds_write_b16 v190, v24 offset:1632
	ds_write_b16_d16_hi v190, v24 offset:1904
	ds_read_b64 v[24:25], v191
	v_lshlrev_b32_e32 v28, 16, v4
	v_lshlrev_b32_e32 v26, 16, v5
	v_and_b32_e32 v27, 0xffff0000, v5
	v_lshlrev_b32_e32 v64, 16, v6
	s_waitcnt lgkmcnt(0)
	v_sub_f32_e32 v29, v29, v24
	v_sub_f32_e32 v28, v28, v24
	v_and_b32_e32 v65, 0xffff0000, v6
	v_lshlrev_b32_e32 v30, 16, v7
	v_and_b32_e32 v31, 0xffff0000, v7
	v_pk_mul_f32 v[28:29], v[24:25], v[28:29] op_sel:[1,0]
	v_sub_f32_e32 v27, v27, v24
	v_sub_f32_e32 v26, v26, v24
	v_pk_fma_f32 v[28:29], v[52:53], v[28:29], v[60:61]
	v_sub_f32_e32 v31, v31, v24
	v_sub_f32_e32 v30, v30, v24
	v_sub_f32_e32 v53, v65, v24
	v_sub_f32_e32 v52, v64, v24
	v_pk_mul_f32 v[26:27], v[24:25], v[26:27] op_sel:[1,0]
	v_pk_mul_f32 v[52:53], v[24:25], v[52:53] op_sel:[1,0]
	v_pk_mul_f32 v[24:25], v[24:25], v[30:31] op_sel:[1,0]
	v_pk_fma_f32 v[26:27], v[54:55], v[26:27], v[62:63]
	v_pk_fma_f32 v[24:25], v[38:39], v[24:25], v[50:51]
	v_cvt_pk_bf16_f32 v28, v28, v29
	v_pk_fma_f32 v[30:31], v[36:37], v[52:53], v[48:49]
	v_cvt_pk_bf16_f32 v26, v26, v27
	s_nop 0
	v_cvt_pk_bf16_f32 v27, v30, v31
	v_cvt_pk_bf16_f32 v24, v24, v25
	ds_write_b16 v192, v28
	ds_write_b16_d16_hi v192, v28 offset:272
	ds_write_b16 v192, v26 offset:544
	ds_write_b16_d16_hi v192, v26 offset:816
	ds_write_b16 v192, v27 offset:1088
	ds_write_b16_d16_hi v192, v27 offset:1360
	ds_write_b16 v192, v24 offset:1632
	ds_write_b16_d16_hi v192, v24 offset:1904
.LBB0_699:
	s_waitcnt vmcnt(2)
	ds_write_b128 v228, v[224:227]
	s_waitcnt lgkmcnt(0)
	s_barrier
	ds_read_b128 v[56:59], v229 offset:0
	ds_read_b128 v[40:43], v229 offset:64
	ds_read_b128 v[44:47], v229 offset:128
	ds_read_b128 v[32:35], v229 offset:192
	ds_read_b32 v154, v223 offset:1024
	global_load_dwordx4 v[84:87], v[112:113], off offset:768
	global_load_dwordx4 v[80:83], v[114:115], off offset:768
	s_and_b64 vcc, exec, s[4:5]
	s_cbranch_vccnz .LBB0_701
	v_lshlrev_b64 v[0:1], 11, v[152:153]
	v_lshl_add_u64 v[0:1], v[122:123], 0, v[0:1]
	global_load_dwordx4 v[0:3], v[0:1], off offset:768

; #define LAS __attribute__((address_space(3)))
; __global__ void __launch_bounds__(NTHR, 2) fwd_megakernel(Args args) {
;     ...
;                 f32x4 a0 = (f32x4){0.f, 0.f, 0.f, 0.f}, a1 = a0;
; #pragma unroll
;                 for (int ks = 0; ks < 4; ++ks) if (ks < nk) {
;                     const int r0 = 16 * (2 * nq) + fr, r1 = r0 + 16, q = ks * 4 + fq;
;                     const bf16x8 x0 = *(const LAS bf16x8*)(Bc + r0 * LDB + ((q ^ ((r0 >> 3) & 15)) * 8)), x1 = *(const LAS bf16x8*)(Bc + r1 * LDB + ((q ^ ((r1 >> 3) & 15)) * 8));
;                     a0 = __builtin_amdgcn_mfma_f32_16x16x32_bf16(x0, cw[ks], a0, 0, 0, 0); a1 = __builtin_amdgcn_mfma_f32_16x16x32_bf16(x1, cw[ks], a1, 0, 0, 0);
;                 }
.LBB0_703:
	s_nop 0
	ds_read_b128 v[60:63], v203 offset:1552
	ds_read_b128 v[72:75], v203 offset:1536
	ds_read_b128 v[68:71], v203 offset:5648
	ds_read_b128 v[76:79], v203 offset:5632
	v_add_co_u32_e32 v24, vcc, 0x18000, v148
	s_waitcnt vmcnt(5)
	v_mov_b64_e32 v[54:55], v[46:47]
	v_addc_co_u32_e32 v25, vcc, 0, v149, vcc
	global_load_dwordx4 v[224:227], v[218:219], off
	v_lshl_add_u64 v[218:219], v[218:219], 0, s[100:101]
	s_nop 0
	s_and_b64 vcc, exec, s[4:5]
	v_mov_b64_e32 v[52:53], v[44:45]
	s_cbranch_vccnz .LBB0_705
	v_add_co_u32_e32 v24, vcc, 0x18000, v148
	s_nop 1
	v_addc_co_u32_e32 v25, vcc, 0, v149, vcc
	s_nop 0
.LBB0_705:
	v_mov_b64_e32 v[38:39], v[34:35]
	s_and_b64 vcc, exec, s[4:5]
	v_mov_b64_e32 v[36:37], v[32:33]
	s_cbranch_vccnz .LBB0_707
	v_add_co_u32_e32 v24, vcc, 0x18000, v148
	s_nop 1
	v_addc_co_u32_e32 v25, vcc, 0, v149, vcc
	s_nop 0
.LBB0_707:
	ds_read_b128 v[24:27], v193
	ds_read_b128 v[28:31], v194
	s_nop 0
	s_and_b64 vcc, exec, s[4:5]
	s_waitcnt lgkmcnt(1)
	v_mfma_f32_16x16x32_bf16 v[24:27], v[24:27], v[56:59], 0
	ds_read_b128 v[88:91], v196
	s_waitcnt lgkmcnt(1)
	v_mfma_f32_16x16x32_bf16 v[56:59], v[28:31], v[56:59], 0
	ds_read_b128 v[28:31], v195
	global_load_dwordx2 v[166:167], v[150:151], off offset:768
	global_load_dwordx2 v[164:165], v[150:151], off offset:800
	s_waitcnt lgkmcnt(0)
	v_mfma_f32_16x16x32_bf16 v[28:31], v[28:31], v[40:43], v[24:27]
	v_mfma_f32_16x16x32_bf16 v[24:27], v[88:91], v[40:43], v[56:59]
	s_cbranch_vccnz .LBB0_709
	ds_read_b128 v[40:43], v197
	s_nop 0
	ds_read_b128 v[56:59], v198
	s_waitcnt lgkmcnt(1)
	v_mfma_f32_16x16x32_bf16 v[28:31], v[40:43], v[44:47], v[28:31]
	s_waitcnt lgkmcnt(0)
	v_mfma_f32_16x16x32_bf16 v[24:27], v[56:59], v[44:47], v[24:27]

; #define LAS __attribute__((address_space(3)))
; __device__ __forceinline__ unsigned cvt_pk_bf16(float lo, float hi) { unsigned r; asm volatile("v_cvt_pk_bf16_f32 %0, %1, %2" : "=v"(r) : "v"(lo), "v"(hi)); return r; }
; __device__ __forceinline__ float bf_lo(unsigned u) { return __uint_as_float(u << 16); }
; __device__ __forceinline__ float bf_hi(unsigned u) { return __uint_as_float(u & 0xffff0000u); }
; __global__ void __launch_bounds__(NTHR, 2) fwd_megakernel(Args args) {
;     ...
;                 for (int k = 0; k < 4; ++k) if (k < nk) { const int j = jb + 32 * k; const u32x4 v = pv[k]; const f32x2 ms = st[j];
;                     const f32x4 x0 = (f32x4){bf_lo(v.x), bf_hi(v.x), bf_lo(v.y), bf_hi(v.y)}, x1 = (f32x4){bf_lo(v.z), bf_hi(v.z), bf_lo(v.w), bf_hi(v.w)};
;                     const f32x4 y0 = (x0 - ms.x) * ms.y * pg0 + pb0, y1 = (x1 - ms.x) * ms.y * pg1 + pb1;
;                     LAS bf16_t* d = Bc + (c8 * 8) * LDB + (j ^ (8 * c8));
;                     const unsigned p0 = cvt_pk_bf16(y0[0], y0[1]), p1 = cvt_pk_bf16(y0[2], y0[3]), p2 = cvt_pk_bf16(y1[0], y1[1]), p3 = cvt_pk_bf16(y1[2], y1[3]);
;                     d[0 * LDB] = (bf16_t)(p0 & 0xffffu); d[1 * LDB] = (bf16_t)(p0 >> 16); d[2 * LDB] = (bf16_t)(p1 & 0xffffu); d[3 * LDB] = (bf16_t)(p1 >> 16);
;                     d[4 * LDB] = (bf16_t)(p2 & 0xffffu); d[5 * LDB] = (bf16_t)(p2 >> 16); d[6 * LDB] = (bf16_t)(p3 & 0xffffu); d[7 * LDB] = (bf16_t)(p3 >> 16); }
;                 bf16x8 cw[4];
; #pragma unroll
;                 for (int ks = 0; ks < 4; ++ks) cw[ks] = pw[ks];
;                 const u32x2 u0 = pu0, u1 = pu1; const float bs = pbs;
;                 __syncthreads();
;                 if (h + 1 < 8) SGU_PREFETCH(h + 1);
.LBB0_711:
	ds_read_b64 v[32:33], v181
	s_waitcnt vmcnt(4)
	v_lshlrev_b32_e32 v40, 16, v84
	v_and_b32_e32 v41, 0xffff0000, v84
	v_lshlrev_b32_e32 v34, 16, v85
	v_and_b32_e32 v35, 0xffff0000, v85
	v_lshlrev_b32_e32 v44, 16, v86
	v_and_b32_e32 v45, 0xffff0000, v86
	v_lshlrev_b32_e32 v42, 16, v87
	v_and_b32_e32 v43, 0xffff0000, v87
	s_waitcnt lgkmcnt(0)
	v_sub_f32_e32 v41, v41, v32
	v_sub_f32_e32 v40, v40, v32
	v_sub_f32_e32 v35, v35, v32
	v_sub_f32_e32 v34, v34, v32
	v_pk_mul_f32 v[40:41], v[32:33], v[40:41] op_sel:[1,0]
	v_sub_f32_e32 v43, v43, v32
	v_sub_f32_e32 v42, v42, v32
	v_sub_f32_e32 v45, v45, v32
	v_sub_f32_e32 v44, v44, v32
	v_pk_mul_f32 v[34:35], v[32:33], v[34:35] op_sel:[1,0]
	s_waitcnt vmcnt(3)
	v_pk_fma_f32 v[40:41], v[72:73], v[40:41], v[76:77]
	v_pk_mul_f32 v[44:45], v[32:33], v[44:45] op_sel:[1,0]
	v_pk_mul_f32 v[32:33], v[32:33], v[42:43] op_sel:[1,0]
	v_pk_fma_f32 v[34:35], v[74:75], v[34:35], v[78:79]
	v_pk_fma_f32 v[32:33], v[62:63], v[32:33], v[70:71]
	v_cvt_pk_bf16_f32 v40, v40, v41
	v_pk_fma_f32 v[42:43], v[60:61], v[44:45], v[68:69]
	v_cvt_pk_bf16_f32 v34, v34, v35
	v_and_b32_e32 v41, 0xffff0000, v80
	v_cvt_pk_bf16_f32 v35, v42, v43
	v_cvt_pk_bf16_f32 v32, v32, v33
	ds_write_b16 v186, v40 offset:34816
	ds_write_b16_d16_hi v186, v40 offset:35088
	ds_write_b16 v186, v34 offset:35360
	ds_write_b16_d16_hi v186, v34 offset:35632
	ds_write_b16 v186, v35 offset:35904
	ds_write_b16_d16_hi v186, v35 offset:36176
	ds_write_b16 v186, v32 offset:36448
	ds_write_b16_d16_hi v186, v32 offset:36720
	ds_read_b64 v[32:33], v187
	v_lshlrev_b32_e32 v40, 16, v80
	v_lshlrev_b32_e32 v34, 16, v81
	v_and_b32_e32 v35, 0xffff0000, v81
	v_lshlrev_b32_e32 v44, 16, v82
	v_and_b32_e32 v45, 0xffff0000, v82
	v_lshlrev_b32_e32 v42, 16, v83
	v_and_b32_e32 v43, 0xffff0000, v83
	s_waitcnt lgkmcnt(0)
	v_sub_f32_e32 v41, v41, v32
	v_sub_f32_e32 v40, v40, v32
	v_sub_f32_e32 v35, v35, v32
	v_sub_f32_e32 v34, v34, v32
	v_pk_mul_f32 v[40:41], v[32:33], v[40:41] op_sel:[1,0]
	v_sub_f32_e32 v43, v43, v32
	v_sub_f32_e32 v42, v42, v32
	v_sub_f32_e32 v45, v45, v32
	v_sub_f32_e32 v44, v44, v32
	v_pk_mul_f32 v[34:35], v[32:33], v[34:35] op_sel:[1,0]
	v_pk_fma_f32 v[40:41], v[72:73], v[40:41], v[76:77]
	v_pk_mul_f32 v[44:45], v[32:33], v[44:45] op_sel:[1,0]
	v_pk_mul_f32 v[32:33], v[32:33], v[42:43] op_sel:[1,0]
	v_pk_fma_f32 v[34:35], v[74:75], v[34:35], v[78:79]
	v_pk_fma_f32 v[32:33], v[62:63], v[32:33], v[70:71]
	v_cvt_pk_bf16_f32 v40, v40, v41
	s_and_b64 vcc, exec, s[4:5]
	v_pk_fma_f32 v[42:43], v[60:61], v[44:45], v[68:69]
	v_cvt_pk_bf16_f32 v34, v34, v35
	s_nop 0
	v_cvt_pk_bf16_f32 v35, v42, v43
	v_cvt_pk_bf16_f32 v32, v32, v33
	ds_write_b16 v188, v40 offset:34816
	ds_write_b16_d16_hi v188, v40 offset:35088
	ds_write_b16 v188, v34 offset:35360
	ds_write_b16_d16_hi v188, v34 offset:35632
	ds_write_b16 v188, v35 offset:35904
	ds_write_b16_d16_hi v188, v35 offset:36176
	ds_write_b16 v188, v32 offset:36448
	ds_write_b16_d16_hi v188, v32 offset:36720
	s_cbranch_vccnz .LBB0_713
	ds_read_b64 v[32:33], v189
	v_lshlrev_b32_e32 v40, 16, v0
	v_and_b32_e32 v41, 0xffff0000, v0
	v_lshlrev_b32_e32 v34, 16, v1
	v_and_b32_e32 v35, 0xffff0000, v1
	v_lshlrev_b32_e32 v44, 16, v2
	v_and_b32_e32 v45, 0xffff0000, v2
	v_lshlrev_b32_e32 v42, 16, v3
	v_and_b32_e32 v43, 0xffff0000, v3
	s_waitcnt lgkmcnt(0)
	v_sub_f32_e32 v41, v41, v32
	v_sub_f32_e32 v40, v40, v32
	v_sub_f32_e32 v35, v35, v32
	v_sub_f32_e32 v34, v34, v32
	v_pk_mul_f32 v[40:41], v[32:33], v[40:41] op_sel:[1,0]
	v_sub_f32_e32 v43, v43, v32
	v_sub_f32_e32 v42, v42, v32
	v_sub_f32_e32 v45, v45, v32
	v_sub_f32_e32 v44, v44, v32
	v_pk_mul_f32 v[34:35], v[32:33], v[34:35] op_sel:[1,0]
	v_pk_fma_f32 v[40:41], v[72:73], v[40:41], v[76:77]
	v_pk_mul_f32 v[44:45], v[32:33], v[44:45] op_sel:[1,0]
	v_pk_mul_f32 v[32:33], v[32:33], v[42:43] op_sel:[1,0]
	v_pk_fma_f32 v[34:35], v[74:75], v[34:35], v[78:79]
	v_pk_fma_f32 v[32:33], v[62:63], v[32:33], v[70:71]
	v_cvt_pk_bf16_f32 v40, v40, v41
	v_pk_fma_f32 v[42:43], v[60:61], v[44:45], v[68:69]
	v_cvt_pk_bf16_f32 v34, v34, v35
	v_and_b32_e32 v41, 0xffff0000, v4
	v_cvt_pk_bf16_f32 v35, v42, v43
	v_cvt_pk_bf16_f32 v32, v32, v33
	ds_write_b16 v190, v40 offset:34816
	ds_write_b16_d16_hi v190, v40 offset:35088
	ds_write_b16 v190, v34 offset:35360
	ds_write_b16_d16_hi v190, v34 offset:35632
	ds_write_b16 v190, v35 offset:35904
	ds_write_b16_d16_hi v190, v35 offset:36176
	ds_write_b16 v190, v32 offset:36448
	ds_write_b16_d16_hi v190, v32 offset:36720
	ds_read_b64 v[32:33], v191
	v_lshlrev_b32_e32 v40, 16, v4
	v_lshlrev_b32_e32 v34, 16, v5
	v_and_b32_e32 v35, 0xffff0000, v5
	v_lshlrev_b32_e32 v44, 16, v6
	v_and_b32_e32 v45, 0xffff0000, v6
	v_lshlrev_b32_e32 v42, 16, v7
	v_and_b32_e32 v43, 0xffff0000, v7
	s_waitcnt lgkmcnt(0)
	v_sub_f32_e32 v41, v41, v32
	v_sub_f32_e32 v40, v40, v32
	v_sub_f32_e32 v35, v35, v32
	v_sub_f32_e32 v34, v34, v32
	v_pk_mul_f32 v[40:41], v[32:33], v[40:41] op_sel:[1,0]
	v_sub_f32_e32 v43, v43, v32
	v_sub_f32_e32 v42, v42, v32
	v_sub_f32_e32 v45, v45, v32
	v_sub_f32_e32 v44, v44, v32
	v_pk_mul_f32 v[34:35], v[32:33], v[34:35] op_sel:[1,0]
	v_pk_fma_f32 v[40:41], v[72:73], v[40:41], v[76:77]
	v_pk_mul_f32 v[44:45], v[32:33], v[44:45] op_sel:[1,0]
	v_pk_mul_f32 v[32:33], v[32:33], v[42:43] op_sel:[1,0]
	v_pk_fma_f32 v[34:35], v[74:75], v[34:35], v[78:79]
	v_pk_fma_f32 v[32:33], v[62:63], v[32:33], v[70:71]
	v_cvt_pk_bf16_f32 v40, v40, v41
	v_pk_fma_f32 v[42:43], v[60:61], v[44:45], v[68:69]
	v_cvt_pk_bf16_f32 v34, v34, v35
	s_nop 0
	v_cvt_pk_bf16_f32 v35, v42, v43
	v_cvt_pk_bf16_f32 v32, v32, v33
	ds_write_b16 v192, v40 offset:34816
	ds_write_b16_d16_hi v192, v40 offset:35088
	ds_write_b16 v192, v34 offset:35360
	ds_write_b16_d16_hi v192, v34 offset:35632
	ds_write_b16 v192, v35 offset:35904
	ds_write_b16_d16_hi v192, v35 offset:36176
	ds_write_b16 v192, v32 offset:36448
	ds_write_b16_d16_hi v192, v32 offset:36720
.LBB0_713:
	s_waitcnt vmcnt(2)
	ds_write_b128 v228, v[224:227] offset:8704
	s_waitcnt lgkmcnt(0)
	s_barrier
	ds_read_b128 v[64:67], v229 offset:8704
	ds_read_b128 v[48:51], v229 offset:8768
	ds_read_b128 v[52:55], v229 offset:8832
	ds_read_b128 v[36:39], v229 offset:8896
	ds_read_b32 v162, v223 offset:1536
	global_load_dwordx4 v[92:95], v[112:113], off offset:1024
	global_load_dwordx4 v[88:91], v[114:115], off offset:1024
	s_and_b64 vcc, exec, s[4:5]
	s_cbranch_vccnz .LBB0_715
	v_lshlrev_b64 v[0:1], 11, v[152:153]
	v_lshl_add_u64 v[0:1], v[122:123], 0, v[0:1]
	global_load_dwordx4 v[0:3], v[0:1], off offset:1024

; #define LAS __attribute__((address_space(3)))
; __global__ void __launch_bounds__(NTHR, 2) fwd_megakernel(Args args) {
;     ...
;                 f32x4 a0 = (f32x4){0.f, 0.f, 0.f, 0.f}, a1 = a0;
; #pragma unroll
;                 for (int ks = 0; ks < 4; ++ks) if (ks < nk) {
;                     const int r0 = 16 * (2 * nq) + fr, r1 = r0 + 16, q = ks * 4 + fq;
;                     const bf16x8 x0 = *(const LAS bf16x8*)(Bc + r0 * LDB + ((q ^ ((r0 >> 3) & 15)) * 8)), x1 = *(const LAS bf16x8*)(Bc + r1 * LDB + ((q ^ ((r1 >> 3) & 15)) * 8));
;                     a0 = __builtin_amdgcn_mfma_f32_16x16x32_bf16(x0, cw[ks], a0, 0, 0, 0); a1 = __builtin_amdgcn_mfma_f32_16x16x32_bf16(x1, cw[ks], a1, 0, 0, 0);
;                 }
.LBB0_717:
	s_nop 0
	ds_read_b128 v[68:71], v203 offset:2064
	ds_read_b128 v[80:83], v203 offset:2048
	ds_read_b128 v[76:79], v203 offset:6160
	ds_read_b128 v[84:87], v203 offset:6144
	v_add_co_u32_e32 v32, vcc, 0x20000, v148
	s_waitcnt vmcnt(5)
	v_mov_b64_e32 v[62:63], v[54:55]
	v_addc_co_u32_e32 v33, vcc, 0, v149, vcc
	global_load_dwordx4 v[224:227], v[218:219], off
	v_lshl_add_u64 v[218:219], v[218:219], 0, s[100:101]
	s_nop 0
	s_and_b64 vcc, exec, s[4:5]
	v_mov_b64_e32 v[60:61], v[52:53]
	s_cbranch_vccnz .LBB0_719
	v_add_co_u32_e32 v32, vcc, 0x20000, v148
	s_nop 1
	v_addc_co_u32_e32 v33, vcc, 0, v149, vcc
	s_nop 0
.LBB0_719:
	v_mov_b64_e32 v[32:33], v[36:37]
	s_and_b64 vcc, exec, s[4:5]
	v_mov_b64_e32 v[34:35], v[38:39]
	s_cbranch_vccnz .LBB0_721
	v_add_co_u32_e32 v32, vcc, 0x20000, v148
	s_nop 1
	v_addc_co_u32_e32 v33, vcc, 0, v149, vcc
	s_nop 0
.LBB0_721:
	ds_read_b128 v[40:43], v193 offset:34816
	ds_read_b128 v[44:47], v194 offset:34816
	s_nop 0
	s_and_b64 vcc, exec, s[4:5]
	s_waitcnt lgkmcnt(1)
	v_mfma_f32_16x16x32_bf16 v[40:43], v[40:43], v[64:67], 0
	ds_read_b128 v[96:99], v196 offset:34816
	s_waitcnt lgkmcnt(1)
	v_mfma_f32_16x16x32_bf16 v[64:67], v[44:47], v[64:67], 0
	ds_read_b128 v[44:47], v195 offset:34816
	global_load_dwordx2 v[172:173], v[150:151], off offset:1024
	global_load_dwordx2 v[170:171], v[150:151], off offset:1056
	s_waitcnt lgkmcnt(0)
	v_mfma_f32_16x16x32_bf16 v[44:47], v[44:47], v[48:51], v[40:43]
	v_mfma_f32_16x16x32_bf16 v[40:43], v[96:99], v[48:51], v[64:67]
	s_cbranch_vccnz .LBB0_723
	ds_read_b128 v[48:51], v197 offset:34816
	s_nop 0
	ds_read_b128 v[64:67], v198 offset:34816
	s_waitcnt lgkmcnt(1)
	v_mfma_f32_16x16x32_bf16 v[44:47], v[48:51], v[52:55], v[44:47]
	s_waitcnt lgkmcnt(0)
	v_mfma_f32_16x16x32_bf16 v[40:43], v[64:67], v[52:55], v[40:43]

; #define LAS __attribute__((address_space(3)))
; __device__ __forceinline__ unsigned cvt_pk_bf16(float lo, float hi) { unsigned r; asm volatile("v_cvt_pk_bf16_f32 %0, %1, %2" : "=v"(r) : "v"(lo), "v"(hi)); return r; }
; __device__ __forceinline__ float bf_lo(unsigned u) { return __uint_as_float(u << 16); }
; __device__ __forceinline__ float bf_hi(unsigned u) { return __uint_as_float(u & 0xffff0000u); }
; __global__ void __launch_bounds__(NTHR, 2) fwd_megakernel(Args args) {
;     ...
;                 for (int k = 0; k < 4; ++k) if (k < nk) { const int j = jb + 32 * k; const u32x4 v = pv[k]; const f32x2 ms = st[j];
;                     const f32x4 x0 = (f32x4){bf_lo(v.x), bf_hi(v.x), bf_lo(v.y), bf_hi(v.y)}, x1 = (f32x4){bf_lo(v.z), bf_hi(v.z), bf_lo(v.w), bf_hi(v.w)};
;                     const f32x4 y0 = (x0 - ms.x) * ms.y * pg0 + pb0, y1 = (x1 - ms.x) * ms.y * pg1 + pb1;
;                     LAS bf16_t* d = Bc + (c8 * 8) * LDB + (j ^ (8 * c8));
;                     const unsigned p0 = cvt_pk_bf16(y0[0], y0[1]), p1 = cvt_pk_bf16(y0[2], y0[3]), p2 = cvt_pk_bf16(y1[0], y1[1]), p3 = cvt_pk_bf16(y1[2], y1[3]);
;                     d[0 * LDB] = (bf16_t)(p0 & 0xffffu); d[1 * LDB] = (bf16_t)(p0 >> 16); d[2 * LDB] = (bf16_t)(p1 & 0xffffu); d[3 * LDB] = (bf16_t)(p1 >> 16);
;                     d[4 * LDB] = (bf16_t)(p2 & 0xffffu); d[5 * LDB] = (bf16_t)(p2 >> 16); d[6 * LDB] = (bf16_t)(p3 & 0xffffu); d[7 * LDB] = (bf16_t)(p3 >> 16); }
;                 bf16x8 cw[4];
; #pragma unroll
;                 for (int ks = 0; ks < 4; ++ks) cw[ks] = pw[ks];
;                 const u32x2 u0 = pu0, u1 = pu1; const float bs = pbs;
;                 __syncthreads();
;                 if (h + 1 < 8) SGU_PREFETCH(h + 1);
.LBB0_725:
	ds_read_b64 v[36:37], v181
	s_waitcnt vmcnt(4)
	v_lshlrev_b32_e32 v48, 16, v92
	v_and_b32_e32 v49, 0xffff0000, v92
	v_lshlrev_b32_e32 v38, 16, v93
	v_and_b32_e32 v39, 0xffff0000, v93
	v_lshlrev_b32_e32 v52, 16, v94
	v_and_b32_e32 v53, 0xffff0000, v94
	v_lshlrev_b32_e32 v50, 16, v95
	v_and_b32_e32 v51, 0xffff0000, v95
	s_waitcnt lgkmcnt(0)
	v_sub_f32_e32 v49, v49, v36
	v_sub_f32_e32 v48, v48, v36
	v_sub_f32_e32 v39, v39, v36
	v_sub_f32_e32 v38, v38, v36
	v_pk_mul_f32 v[48:49], v[36:37], v[48:49] op_sel:[1,0]
	v_sub_f32_e32 v51, v51, v36
	v_sub_f32_e32 v50, v50, v36
	v_sub_f32_e32 v53, v53, v36
	v_sub_f32_e32 v52, v52, v36
	v_pk_mul_f32 v[38:39], v[36:37], v[38:39] op_sel:[1,0]
	s_waitcnt vmcnt(3)
	v_pk_fma_f32 v[48:49], v[80:81], v[48:49], v[84:85]
	v_pk_mul_f32 v[52:53], v[36:37], v[52:53] op_sel:[1,0]
	v_pk_mul_f32 v[36:37], v[36:37], v[50:51] op_sel:[1,0]
	v_pk_fma_f32 v[38:39], v[82:83], v[38:39], v[86:87]
	v_pk_fma_f32 v[36:37], v[70:71], v[36:37], v[78:79]
	v_cvt_pk_bf16_f32 v48, v48, v49
	v_pk_fma_f32 v[50:51], v[68:69], v[52:53], v[76:77]
	v_cvt_pk_bf16_f32 v38, v38, v39
	v_and_b32_e32 v49, 0xffff0000, v88
	v_cvt_pk_bf16_f32 v39, v50, v51
	v_cvt_pk_bf16_f32 v36, v36, v37
	ds_write_b16 v186, v48
	ds_write_b16_d16_hi v186, v48 offset:272
	ds_write_b16 v186, v38 offset:544
	ds_write_b16_d16_hi v186, v38 offset:816
	ds_write_b16 v186, v39 offset:1088
	ds_write_b16_d16_hi v186, v39 offset:1360
	ds_write_b16 v186, v36 offset:1632
	ds_write_b16_d16_hi v186, v36 offset:1904
	ds_read_b64 v[36:37], v187
	v_lshlrev_b32_e32 v48, 16, v88
	v_lshlrev_b32_e32 v38, 16, v89
	v_and_b32_e32 v39, 0xffff0000, v89
	v_lshlrev_b32_e32 v52, 16, v90
	v_and_b32_e32 v53, 0xffff0000, v90
	v_lshlrev_b32_e32 v50, 16, v91
	v_and_b32_e32 v51, 0xffff0000, v91
	s_waitcnt lgkmcnt(0)
	v_sub_f32_e32 v49, v49, v36
	v_sub_f32_e32 v48, v48, v36
	v_sub_f32_e32 v39, v39, v36
	v_sub_f32_e32 v38, v38, v36
	v_pk_mul_f32 v[48:49], v[36:37], v[48:49] op_sel:[1,0]
	v_sub_f32_e32 v51, v51, v36
	v_sub_f32_e32 v50, v50, v36
	v_sub_f32_e32 v53, v53, v36
	v_sub_f32_e32 v52, v52, v36
	v_pk_mul_f32 v[38:39], v[36:37], v[38:39] op_sel:[1,0]
	v_pk_fma_f32 v[48:49], v[80:81], v[48:49], v[84:85]
	v_pk_mul_f32 v[52:53], v[36:37], v[52:53] op_sel:[1,0]
	v_pk_mul_f32 v[36:37], v[36:37], v[50:51] op_sel:[1,0]
	v_pk_fma_f32 v[38:39], v[82:83], v[38:39], v[86:87]
	v_pk_fma_f32 v[36:37], v[70:71], v[36:37], v[78:79]
	v_cvt_pk_bf16_f32 v48, v48, v49
	s_and_b64 vcc, exec, s[4:5]
	v_pk_fma_f32 v[50:51], v[68:69], v[52:53], v[76:77]
	v_cvt_pk_bf16_f32 v38, v38, v39
	s_nop 0
	v_cvt_pk_bf16_f32 v39, v50, v51
	v_cvt_pk_bf16_f32 v36, v36, v37
	ds_write_b16 v188, v48
	ds_write_b16_d16_hi v188, v48 offset:272
	ds_write_b16 v188, v38 offset:544
	ds_write_b16_d16_hi v188, v38 offset:816
	ds_write_b16 v188, v39 offset:1088
	ds_write_b16_d16_hi v188, v39 offset:1360
	ds_write_b16 v188, v36 offset:1632
	ds_write_b16_d16_hi v188, v36 offset:1904
	s_cbranch_vccnz .LBB0_727
	ds_read_b64 v[36:37], v189
	v_lshlrev_b32_e32 v48, 16, v0
	v_and_b32_e32 v49, 0xffff0000, v0
	v_lshlrev_b32_e32 v38, 16, v1
	v_and_b32_e32 v39, 0xffff0000, v1
	v_lshlrev_b32_e32 v52, 16, v2
	v_and_b32_e32 v53, 0xffff0000, v2
	v_lshlrev_b32_e32 v50, 16, v3
	v_and_b32_e32 v51, 0xffff0000, v3
	s_waitcnt lgkmcnt(0)
	v_sub_f32_e32 v49, v49, v36
	v_sub_f32_e32 v48, v48, v36
	v_sub_f32_e32 v39, v39, v36
	v_sub_f32_e32 v38, v38, v36
	v_pk_mul_f32 v[48:49], v[36:37], v[48:49] op_sel:[1,0]
	v_sub_f32_e32 v51, v51, v36
	v_sub_f32_e32 v50, v50, v36
	v_sub_f32_e32 v53, v53, v36
	v_sub_f32_e32 v52, v52, v36
	v_pk_mul_f32 v[38:39], v[36:37], v[38:39] op_sel:[1,0]
	v_pk_fma_f32 v[48:49], v[80:81], v[48:49], v[84:85]
	v_pk_mul_f32 v[52:53], v[36:37], v[52:53] op_sel:[1,0]
	v_pk_mul_f32 v[36:37], v[36:37], v[50:51] op_sel:[1,0]
	v_pk_fma_f32 v[38:39], v[82:83], v[38:39], v[86:87]
	v_pk_fma_f32 v[36:37], v[70:71], v[36:37], v[78:79]
	v_cvt_pk_bf16_f32 v48, v48, v49
	v_pk_fma_f32 v[50:51], v[68:69], v[52:53], v[76:77]
	v_cvt_pk_bf16_f32 v38, v38, v39
	v_and_b32_e32 v49, 0xffff0000, v4
	v_cvt_pk_bf16_f32 v39, v50, v51
	v_cvt_pk_bf16_f32 v36, v36, v37
	ds_write_b16 v190, v48
	ds_write_b16_d16_hi v190, v48 offset:272
	ds_write_b16 v190, v38 offset:544
	ds_write_b16_d16_hi v190, v38 offset:816
	ds_write_b16 v190, v39 offset:1088
	ds_write_b16_d16_hi v190, v39 offset:1360
	ds_write_b16 v190, v36 offset:1632
	ds_write_b16_d16_hi v190, v36 offset:1904
	ds_read_b64 v[36:37], v191
	v_lshlrev_b32_e32 v48, 16, v4
	v_lshlrev_b32_e32 v38, 16, v5
	v_and_b32_e32 v39, 0xffff0000, v5
	v_lshlrev_b32_e32 v52, 16, v6
	v_and_b32_e32 v53, 0xffff0000, v6
	v_lshlrev_b32_e32 v50, 16, v7
	v_and_b32_e32 v51, 0xffff0000, v7
	s_waitcnt lgkmcnt(0)
	v_sub_f32_e32 v49, v49, v36
	v_sub_f32_e32 v48, v48, v36
	v_sub_f32_e32 v39, v39, v36
	v_sub_f32_e32 v38, v38, v36
	v_pk_mul_f32 v[48:49], v[36:37], v[48:49] op_sel:[1,0]
	v_sub_f32_e32 v51, v51, v36
	v_sub_f32_e32 v50, v50, v36
	v_sub_f32_e32 v53, v53, v36
	v_sub_f32_e32 v52, v52, v36
	v_pk_mul_f32 v[38:39], v[36:37], v[38:39] op_sel:[1,0]
	v_pk_fma_f32 v[48:49], v[80:81], v[48:49], v[84:85]
	v_pk_mul_f32 v[52:53], v[36:37], v[52:53] op_sel:[1,0]
	v_pk_mul_f32 v[36:37], v[36:37], v[50:51] op_sel:[1,0]
	v_pk_fma_f32 v[38:39], v[82:83], v[38:39], v[86:87]
	v_pk_fma_f32 v[36:37], v[70:71], v[36:37], v[78:79]
	v_cvt_pk_bf16_f32 v48, v48, v49
	v_pk_fma_f32 v[50:51], v[68:69], v[52:53], v[76:77]
	v_cvt_pk_bf16_f32 v38, v38, v39
	s_nop 0
	v_cvt_pk_bf16_f32 v39, v50, v51
	v_cvt_pk_bf16_f32 v36, v36, v37
	ds_write_b16 v192, v48
	ds_write_b16_d16_hi v192, v48 offset:272
	ds_write_b16 v192, v38 offset:544
	ds_write_b16_d16_hi v192, v38 offset:816
	ds_write_b16 v192, v39 offset:1088
	ds_write_b16_d16_hi v192, v39 offset:1360
	ds_write_b16 v192, v36 offset:1632
	ds_write_b16_d16_hi v192, v36 offset:1904
.LBB0_727:
	s_waitcnt vmcnt(2)
	ds_write_b128 v228, v[224:227]
	s_waitcnt lgkmcnt(0)
	s_barrier
	ds_read_b128 v[72:75], v229 offset:0
	ds_read_b128 v[56:59], v229 offset:64
	ds_read_b128 v[60:63], v229 offset:128
	ds_read_b128 v[32:35], v229 offset:192
	ds_read_b32 v168, v223 offset:2048
	global_load_dwordx4 v[100:103], v[112:113], off offset:1280
	global_load_dwordx4 v[96:99], v[114:115], off offset:1280
	s_and_b64 vcc, exec, s[4:5]
	s_cbranch_vccnz .LBB0_729
	v_lshlrev_b64 v[0:1], 11, v[152:153]
	v_lshl_add_u64 v[0:1], v[122:123], 0, v[0:1]
	global_load_dwordx4 v[0:3], v[0:1], off offset:1280

; #define LAS __attribute__((address_space(3)))
; __global__ void __launch_bounds__(NTHR, 2) fwd_megakernel(Args args) {
;     ...
;                 f32x4 a0 = (f32x4){0.f, 0.f, 0.f, 0.f}, a1 = a0;
; #pragma unroll
;                 for (int ks = 0; ks < 4; ++ks) if (ks < nk) {
;                     const int r0 = 16 * (2 * nq) + fr, r1 = r0 + 16, q = ks * 4 + fq;
;                     const bf16x8 x0 = *(const LAS bf16x8*)(Bc + r0 * LDB + ((q ^ ((r0 >> 3) & 15)) * 8)), x1 = *(const LAS bf16x8*)(Bc + r1 * LDB + ((q ^ ((r1 >> 3) & 15)) * 8));
;                     a0 = __builtin_amdgcn_mfma_f32_16x16x32_bf16(x0, cw[ks], a0, 0, 0, 0); a1 = __builtin_amdgcn_mfma_f32_16x16x32_bf16(x1, cw[ks], a1, 0, 0, 0);
;                 }
.LBB0_731:
	s_nop 0
	ds_read_b128 v[76:79], v203 offset:2576
	ds_read_b128 v[88:91], v203 offset:2560
	ds_read_b128 v[80:83], v203 offset:6672
	ds_read_b128 v[92:95], v203 offset:6656
	v_add_co_u32_e32 v36, vcc, 0x28000, v148
	s_waitcnt vmcnt(5)
	v_mov_b64_e32 v[70:71], v[62:63]
	v_addc_co_u32_e32 v37, vcc, 0, v149, vcc
	global_load_dwordx4 v[224:227], v[218:219], off
	v_lshl_add_u64 v[218:219], v[218:219], 0, s[100:101]
	s_nop 0
	s_and_b64 vcc, exec, s[4:5]
	v_mov_b64_e32 v[68:69], v[60:61]
	s_cbranch_vccnz .LBB0_733
	v_add_co_u32_e32 v36, vcc, 0x28000, v148
	s_nop 1
	v_addc_co_u32_e32 v37, vcc, 0, v149, vcc
	s_nop 0
.LBB0_733:
	v_mov_b64_e32 v[38:39], v[34:35]
	s_and_b64 vcc, exec, s[4:5]
	v_mov_b64_e32 v[36:37], v[32:33]
	s_cbranch_vccnz .LBB0_735
	v_add_co_u32_e32 v36, vcc, 0x28000, v148
	s_nop 1
	v_addc_co_u32_e32 v37, vcc, 0, v149, vcc
	s_nop 0
.LBB0_735:
	ds_read_b128 v[48:51], v193
	ds_read_b128 v[52:55], v194
	s_nop 0
	s_and_b64 vcc, exec, s[4:5]
	s_waitcnt lgkmcnt(1)
	v_mfma_f32_16x16x32_bf16 v[48:51], v[48:51], v[72:75], 0
	ds_read_b128 v[104:107], v196
	s_waitcnt lgkmcnt(1)
	v_mfma_f32_16x16x32_bf16 v[72:75], v[52:55], v[72:75], 0
	ds_read_b128 v[52:55], v195
	global_load_dwordx2 v[178:179], v[150:151], off offset:1280
	global_load_dwordx2 v[176:177], v[150:151], off offset:1312
	s_waitcnt lgkmcnt(0)
	v_mfma_f32_16x16x32_bf16 v[52:55], v[52:55], v[56:59], v[48:51]
	v_mfma_f32_16x16x32_bf16 v[48:51], v[104:107], v[56:59], v[72:75]
	s_cbranch_vccnz .LBB0_737
	ds_read_b128 v[56:59], v197
	s_nop 0
	ds_read_b128 v[72:75], v198
	s_waitcnt lgkmcnt(1)
	v_mfma_f32_16x16x32_bf16 v[52:55], v[56:59], v[60:63], v[52:55]
	s_waitcnt lgkmcnt(0)
	v_mfma_f32_16x16x32_bf16 v[48:51], v[72:75], v[60:63], v[48:51]

; #define LAS __attribute__((address_space(3)))
; __device__ __forceinline__ unsigned cvt_pk_bf16(float lo, float hi) { unsigned r; asm volatile("v_cvt_pk_bf16_f32 %0, %1, %2" : "=v"(r) : "v"(lo), "v"(hi)); return r; }
; __device__ __forceinline__ float bf_lo(unsigned u) { return __uint_as_float(u << 16); }
; __device__ __forceinline__ float bf_hi(unsigned u) { return __uint_as_float(u & 0xffff0000u); }
; __global__ void __launch_bounds__(NTHR, 2) fwd_megakernel(Args args) {
;     ...
;                 for (int k = 0; k < 4; ++k) if (k < nk) { const int j = jb + 32 * k; const u32x4 v = pv[k]; const f32x2 ms = st[j];
;                     const f32x4 x0 = (f32x4){bf_lo(v.x), bf_hi(v.x), bf_lo(v.y), bf_hi(v.y)}, x1 = (f32x4){bf_lo(v.z), bf_hi(v.z), bf_lo(v.w), bf_hi(v.w)};
;                     const f32x4 y0 = (x0 - ms.x) * ms.y * pg0 + pb0, y1 = (x1 - ms.x) * ms.y * pg1 + pb1;
;                     LAS bf16_t* d = Bc + (c8 * 8) * LDB + (j ^ (8 * c8));
;                     const unsigned p0 = cvt_pk_bf16(y0[0], y0[1]), p1 = cvt_pk_bf16(y0[2], y0[3]), p2 = cvt_pk_bf16(y1[0], y1[1]), p3 = cvt_pk_bf16(y1[2], y1[3]);
;                     d[0 * LDB] = (bf16_t)(p0 & 0xffffu); d[1 * LDB] = (bf16_t)(p0 >> 16); d[2 * LDB] = (bf16_t)(p1 & 0xffffu); d[3 * LDB] = (bf16_t)(p1 >> 16);
;                     d[4 * LDB] = (bf16_t)(p2 & 0xffffu); d[5 * LDB] = (bf16_t)(p2 >> 16); d[6 * LDB] = (bf16_t)(p3 & 0xffffu); d[7 * LDB] = (bf16_t)(p3 >> 16); }
;                 bf16x8 cw[4];
; #pragma unroll
;                 for (int ks = 0; ks < 4; ++ks) cw[ks] = pw[ks];
;                 const u32x2 u0 = pu0, u1 = pu1; const float bs = pbs;
;                 __syncthreads();
;                 if (h + 1 < 8) SGU_PREFETCH(h + 1);
.LBB0_739:
	ds_read_b64 v[32:33], v181
	s_waitcnt vmcnt(4)
	v_lshlrev_b32_e32 v56, 16, v100
	v_and_b32_e32 v57, 0xffff0000, v100
	v_lshlrev_b32_e32 v34, 16, v101
	v_and_b32_e32 v35, 0xffff0000, v101
	v_lshlrev_b32_e32 v60, 16, v102
	v_and_b32_e32 v61, 0xffff0000, v102
	v_lshlrev_b32_e32 v58, 16, v103
	v_and_b32_e32 v59, 0xffff0000, v103
	s_waitcnt lgkmcnt(0)
	v_sub_f32_e32 v57, v57, v32
	v_sub_f32_e32 v56, v56, v32
	v_sub_f32_e32 v35, v35, v32
	v_sub_f32_e32 v34, v34, v32
	v_pk_mul_f32 v[56:57], v[32:33], v[56:57] op_sel:[1,0]
	v_sub_f32_e32 v59, v59, v32
	v_sub_f32_e32 v58, v58, v32
	v_sub_f32_e32 v61, v61, v32
	v_sub_f32_e32 v60, v60, v32
	v_pk_mul_f32 v[34:35], v[32:33], v[34:35] op_sel:[1,0]
	s_waitcnt vmcnt(3)
	v_pk_fma_f32 v[56:57], v[88:89], v[56:57], v[92:93]
	v_pk_mul_f32 v[60:61], v[32:33], v[60:61] op_sel:[1,0]
	v_pk_mul_f32 v[32:33], v[32:33], v[58:59] op_sel:[1,0]
	v_pk_fma_f32 v[34:35], v[90:91], v[34:35], v[94:95]
	v_pk_fma_f32 v[32:33], v[78:79], v[32:33], v[82:83]
	v_cvt_pk_bf16_f32 v56, v56, v57
	v_pk_fma_f32 v[58:59], v[76:77], v[60:61], v[80:81]
	v_cvt_pk_bf16_f32 v34, v34, v35
	v_and_b32_e32 v57, 0xffff0000, v96
	v_cvt_pk_bf16_f32 v35, v58, v59
	v_cvt_pk_bf16_f32 v32, v32, v33
	ds_write_b16 v186, v56 offset:34816
	ds_write_b16_d16_hi v186, v56 offset:35088
	ds_write_b16 v186, v34 offset:35360
	ds_write_b16_d16_hi v186, v34 offset:35632
	ds_write_b16 v186, v35 offset:35904
	ds_write_b16_d16_hi v186, v35 offset:36176
	ds_write_b16 v186, v32 offset:36448
	ds_write_b16_d16_hi v186, v32 offset:36720
	ds_read_b64 v[32:33], v187
	v_lshlrev_b32_e32 v56, 16, v96
	v_lshlrev_b32_e32 v34, 16, v97
	v_and_b32_e32 v35, 0xffff0000, v97
	v_lshlrev_b32_e32 v60, 16, v98
	v_and_b32_e32 v61, 0xffff0000, v98
	v_lshlrev_b32_e32 v58, 16, v99
	v_and_b32_e32 v59, 0xffff0000, v99
	s_waitcnt lgkmcnt(0)
	v_sub_f32_e32 v57, v57, v32
	v_sub_f32_e32 v56, v56, v32
	v_sub_f32_e32 v35, v35, v32
	v_sub_f32_e32 v34, v34, v32
	v_pk_mul_f32 v[56:57], v[32:33], v[56:57] op_sel:[1,0]
	v_sub_f32_e32 v59, v59, v32
	v_sub_f32_e32 v58, v58, v32
	v_sub_f32_e32 v61, v61, v32
	v_sub_f32_e32 v60, v60, v32
	v_pk_mul_f32 v[34:35], v[32:33], v[34:35] op_sel:[1,0]
	v_pk_fma_f32 v[56:57], v[88:89], v[56:57], v[92:93]
	v_pk_mul_f32 v[60:61], v[32:33], v[60:61] op_sel:[1,0]
	v_pk_mul_f32 v[32:33], v[32:33], v[58:59] op_sel:[1,0]
	v_pk_fma_f32 v[34:35], v[90:91], v[34:35], v[94:95]
	v_pk_fma_f32 v[32:33], v[78:79], v[32:33], v[82:83]
	v_cvt_pk_bf16_f32 v56, v56, v57
	s_and_b64 vcc, exec, s[4:5]
	v_pk_fma_f32 v[58:59], v[76:77], v[60:61], v[80:81]
	v_cvt_pk_bf16_f32 v34, v34, v35
	s_nop 0
	v_cvt_pk_bf16_f32 v35, v58, v59
	v_cvt_pk_bf16_f32 v32, v32, v33
	ds_write_b16 v188, v56 offset:34816
	ds_write_b16_d16_hi v188, v56 offset:35088
	ds_write_b16 v188, v34 offset:35360
	ds_write_b16_d16_hi v188, v34 offset:35632
	ds_write_b16 v188, v35 offset:35904
	ds_write_b16_d16_hi v188, v35 offset:36176
	ds_write_b16 v188, v32 offset:36448
	ds_write_b16_d16_hi v188, v32 offset:36720
	s_cbranch_vccnz .LBB0_741
	ds_read_b64 v[32:33], v189
	v_lshlrev_b32_e32 v56, 16, v0
	v_and_b32_e32 v57, 0xffff0000, v0
	v_lshlrev_b32_e32 v34, 16, v1
	v_and_b32_e32 v35, 0xffff0000, v1
	v_lshlrev_b32_e32 v60, 16, v2
	v_and_b32_e32 v61, 0xffff0000, v2
	v_lshlrev_b32_e32 v58, 16, v3
	v_and_b32_e32 v59, 0xffff0000, v3
	s_waitcnt lgkmcnt(0)
	v_sub_f32_e32 v57, v57, v32
	v_sub_f32_e32 v56, v56, v32
	v_sub_f32_e32 v35, v35, v32
	v_sub_f32_e32 v34, v34, v32
	v_pk_mul_f32 v[56:57], v[32:33], v[56:57] op_sel:[1,0]
	v_sub_f32_e32 v59, v59, v32
	v_sub_f32_e32 v58, v58, v32
	v_sub_f32_e32 v61, v61, v32
	v_sub_f32_e32 v60, v60, v32
	v_pk_mul_f32 v[34:35], v[32:33], v[34:35] op_sel:[1,0]
	v_pk_fma_f32 v[56:57], v[88:89], v[56:57], v[92:93]
	v_pk_mul_f32 v[60:61], v[32:33], v[60:61] op_sel:[1,0]
	v_pk_mul_f32 v[32:33], v[32:33], v[58:59] op_sel:[1,0]
	v_pk_fma_f32 v[34:35], v[90:91], v[34:35], v[94:95]
	v_pk_fma_f32 v[32:33], v[78:79], v[32:33], v[82:83]
	v_cvt_pk_bf16_f32 v56, v56, v57
	v_pk_fma_f32 v[58:59], v[76:77], v[60:61], v[80:81]
	v_cvt_pk_bf16_f32 v34, v34, v35
	v_and_b32_e32 v57, 0xffff0000, v4
	v_cvt_pk_bf16_f32 v35, v58, v59
	v_cvt_pk_bf16_f32 v32, v32, v33
	ds_write_b16 v190, v56 offset:34816
	ds_write_b16_d16_hi v190, v56 offset:35088
	ds_write_b16 v190, v34 offset:35360
	ds_write_b16_d16_hi v190, v34 offset:35632
	ds_write_b16 v190, v35 offset:35904
	ds_write_b16_d16_hi v190, v35 offset:36176
	ds_write_b16 v190, v32 offset:36448
	ds_write_b16_d16_hi v190, v32 offset:36720
	ds_read_b64 v[32:33], v191
	v_lshlrev_b32_e32 v56, 16, v4
	v_lshlrev_b32_e32 v34, 16, v5
	v_and_b32_e32 v35, 0xffff0000, v5
	v_lshlrev_b32_e32 v60, 16, v6
	v_and_b32_e32 v61, 0xffff0000, v6
	v_lshlrev_b32_e32 v58, 16, v7
	v_and_b32_e32 v59, 0xffff0000, v7
	s_waitcnt lgkmcnt(0)
	v_sub_f32_e32 v57, v57, v32
	v_sub_f32_e32 v56, v56, v32
	v_sub_f32_e32 v35, v35, v32
	v_sub_f32_e32 v34, v34, v32
	v_pk_mul_f32 v[56:57], v[32:33], v[56:57] op_sel:[1,0]
	v_sub_f32_e32 v59, v59, v32
	v_sub_f32_e32 v58, v58, v32
	v_sub_f32_e32 v61, v61, v32
	v_sub_f32_e32 v60, v60, v32
	v_pk_mul_f32 v[34:35], v[32:33], v[34:35] op_sel:[1,0]
	v_pk_fma_f32 v[56:57], v[88:89], v[56:57], v[92:93]
	v_pk_mul_f32 v[60:61], v[32:33], v[60:61] op_sel:[1,0]
	v_pk_mul_f32 v[32:33], v[32:33], v[58:59] op_sel:[1,0]
	v_pk_fma_f32 v[34:35], v[90:91], v[34:35], v[94:95]
	v_pk_fma_f32 v[32:33], v[78:79], v[32:33], v[82:83]
	v_cvt_pk_bf16_f32 v56, v56, v57
	v_pk_fma_f32 v[58:59], v[76:77], v[60:61], v[80:81]
	v_cvt_pk_bf16_f32 v34, v34, v35
	s_nop 0
	v_cvt_pk_bf16_f32 v35, v58, v59
	v_cvt_pk_bf16_f32 v32, v32, v33
	ds_write_b16 v192, v56 offset:34816
	ds_write_b16_d16_hi v192, v56 offset:35088
	ds_write_b16 v192, v34 offset:35360
	ds_write_b16_d16_hi v192, v34 offset:35632
	ds_write_b16 v192, v35 offset:35904
	ds_write_b16_d16_hi v192, v35 offset:36176
	ds_write_b16 v192, v32 offset:36448
	ds_write_b16_d16_hi v192, v32 offset:36720
.LBB0_741:
	s_waitcnt vmcnt(2)
	ds_write_b128 v228, v[224:227] offset:8704
	s_waitcnt lgkmcnt(0)
	s_barrier
	ds_read_b128 v[84:87], v229 offset:8704
	ds_read_b128 v[64:67], v229 offset:8768
	ds_read_b128 v[68:71], v229 offset:8832
	ds_read_b128 v[36:39], v229 offset:8896
	ds_read_b32 v174, v223 offset:2560
	global_load_dwordx4 v[108:111], v[112:113], off offset:1536
	global_load_dwordx4 v[104:107], v[114:115], off offset:1536
	s_and_b64 vcc, exec, s[4:5]
	s_cbranch_vccnz .LBB0_743
	v_lshlrev_b64 v[0:1], 11, v[152:153]
	v_lshl_add_u64 v[0:1], v[122:123], 0, v[0:1]
	global_load_dwordx4 v[0:3], v[0:1], off offset:1536

; #define LAS __attribute__((address_space(3)))
; __global__ void __launch_bounds__(NTHR, 2) fwd_megakernel(Args args) {
;     ...
;                 f32x4 a0 = (f32x4){0.f, 0.f, 0.f, 0.f}, a1 = a0;
; #pragma unroll
;                 for (int ks = 0; ks < 4; ++ks) if (ks < nk) {
;                     const int r0 = 16 * (2 * nq) + fr, r1 = r0 + 16, q = ks * 4 + fq;
;                     const bf16x8 x0 = *(const LAS bf16x8*)(Bc + r0 * LDB + ((q ^ ((r0 >> 3) & 15)) * 8)), x1 = *(const LAS bf16x8*)(Bc + r1 * LDB + ((q ^ ((r1 >> 3) & 15)) * 8));
;                     a0 = __builtin_amdgcn_mfma_f32_16x16x32_bf16(x0, cw[ks], a0, 0, 0, 0); a1 = __builtin_amdgcn_mfma_f32_16x16x32_bf16(x1, cw[ks], a1, 0, 0, 0);
;                 }
.LBB0_745:
	s_nop 0
	ds_read_b128 v[32:35], v203 offset:3088
	ds_read_b128 v[96:99], v203 offset:3072
	ds_read_b128 v[92:95], v203 offset:7184
	ds_read_b128 v[100:103], v203 offset:7168
	v_add_co_u32_e32 v56, vcc, 0x30000, v148
	s_waitcnt vmcnt(5)
	v_mov_b64_e32 v[82:83], v[70:71]
	v_addc_co_u32_e32 v57, vcc, 0, v149, vcc
	global_load_dwordx4 v[224:227], v[218:219], off
	v_lshl_add_u64 v[218:219], v[218:219], 0, s[100:101]
	s_nop 0
	s_and_b64 vcc, exec, s[4:5]
	v_mov_b64_e32 v[80:81], v[68:69]
	s_cbranch_vccnz .LBB0_747
	v_add_co_u32_e32 v56, vcc, 0x30000, v148
	s_nop 1
	v_addc_co_u32_e32 v57, vcc, 0, v149, vcc
	s_nop 0
.LBB0_747:
	v_mov_b64_e32 v[74:75], v[38:39]
	s_and_b64 vcc, exec, s[4:5]
	v_mov_b64_e32 v[72:73], v[36:37]
	s_cbranch_vccnz .LBB0_749
	v_add_co_u32_e32 v56, vcc, 0x30000, v148
	s_nop 1
	v_addc_co_u32_e32 v57, vcc, 0, v149, vcc
	s_nop 0
.LBB0_749:
	ds_read_b128 v[56:59], v193 offset:34816
	ds_read_b128 v[60:63], v194 offset:34816
	s_nop 0
	s_and_b64 vcc, exec, s[4:5]
	s_waitcnt lgkmcnt(1)
	v_mfma_f32_16x16x32_bf16 v[56:59], v[56:59], v[84:87], 0
	ds_read_b128 v[116:119], v196 offset:34816
	s_waitcnt lgkmcnt(1)
	v_mfma_f32_16x16x32_bf16 v[84:87], v[60:63], v[84:87], 0
	ds_read_b128 v[60:63], v195 offset:34816
	global_load_dwordx2 v[184:185], v[150:151], off offset:1536
	global_load_dwordx2 v[182:183], v[150:151], off offset:1568
	s_waitcnt lgkmcnt(0)
	v_mfma_f32_16x16x32_bf16 v[60:63], v[60:63], v[64:67], v[56:59]
	v_mfma_f32_16x16x32_bf16 v[56:59], v[116:119], v[64:67], v[84:87]
	s_cbranch_vccnz .LBB0_751
	ds_read_b128 v[64:67], v197 offset:34816
	s_nop 0
	ds_read_b128 v[84:87], v198 offset:34816
	s_waitcnt lgkmcnt(1)
	v_mfma_f32_16x16x32_bf16 v[60:63], v[64:67], v[68:71], v[60:63]
	s_waitcnt lgkmcnt(0)
	v_mfma_f32_16x16x32_bf16 v[56:59], v[84:87], v[68:71], v[56:59]

; #define LAS __attribute__((address_space(3)))
; __device__ __forceinline__ unsigned cvt_pk_bf16(float lo, float hi) { unsigned r; asm volatile("v_cvt_pk_bf16_f32 %0, %1, %2" : "=v"(r) : "v"(lo), "v"(hi)); return r; }
; __device__ __forceinline__ float bf_lo(unsigned u) { return __uint_as_float(u << 16); }
; __device__ __forceinline__ float bf_hi(unsigned u) { return __uint_as_float(u & 0xffff0000u); }
; __global__ void __launch_bounds__(NTHR, 2) fwd_megakernel(Args args) {
;     ...
;                 LAS bf16_t* Bc = Bt + (h & 1) * (128 * LDB);
; #pragma unroll
;                 for (int k = 0; k < 4; ++k) if (k < nk) { const int j = jb + 32 * k; const u32x4 v = pv[k]; const f32x2 ms = st[j];
;                     const f32x4 x0 = (f32x4){bf_lo(v.x), bf_hi(v.x), bf_lo(v.y), bf_hi(v.y)}, x1 = (f32x4){bf_lo(v.z), bf_hi(v.z), bf_lo(v.w), bf_hi(v.w)};
;                     const f32x4 y0 = (x0 - ms.x) * ms.y * pg0 + pb0, y1 = (x1 - ms.x) * ms.y * pg1 + pb1;
;                     LAS bf16_t* d = Bc + (c8 * 8) * LDB + (j ^ (8 * c8));
;                     const unsigned p0 = cvt_pk_bf16(y0[0], y0[1]), p1 = cvt_pk_bf16(y0[2], y0[3]), p2 = cvt_pk_bf16(y1[0], y1[1]), p3 = cvt_pk_bf16(y1[2], y1[3]);
;                     d[0 * LDB] = (bf16_t)(p0 & 0xffffu); d[1 * LDB] = (bf16_t)(p0 >> 16); d[2 * LDB] = (bf16_t)(p1 & 0xffffu); d[3 * LDB] = (bf16_t)(p1 >> 16);
;                     d[4 * LDB] = (bf16_t)(p2 & 0xffffu); d[5 * LDB] = (bf16_t)(p2 >> 16); d[6 * LDB] = (bf16_t)(p3 & 0xffffu); d[7 * LDB] = (bf16_t)(p3 >> 16); }
.LBB0_753:
	ds_read_b64 v[36:37], v181
	s_waitcnt vmcnt(4)
	v_lshlrev_b32_e32 v64, 16, v108
	v_and_b32_e32 v65, 0xffff0000, v108
	v_lshlrev_b32_e32 v38, 16, v109
	v_and_b32_e32 v39, 0xffff0000, v109
	v_lshlrev_b32_e32 v68, 16, v110
	v_and_b32_e32 v69, 0xffff0000, v110
	v_lshlrev_b32_e32 v66, 16, v111
	v_and_b32_e32 v67, 0xffff0000, v111
	s_waitcnt lgkmcnt(0)
	v_sub_f32_e32 v65, v65, v36
	v_sub_f32_e32 v64, v64, v36
	v_sub_f32_e32 v39, v39, v36
	v_sub_f32_e32 v38, v38, v36
	v_pk_mul_f32 v[64:65], v[36:37], v[64:65] op_sel:[1,0]
	v_sub_f32_e32 v67, v67, v36
	v_sub_f32_e32 v66, v66, v36
	v_sub_f32_e32 v69, v69, v36
	v_sub_f32_e32 v68, v68, v36
	v_pk_mul_f32 v[38:39], v[36:37], v[38:39] op_sel:[1,0]
	s_waitcnt vmcnt(3)
	v_pk_fma_f32 v[64:65], v[96:97], v[64:65], v[100:101]
	v_pk_mul_f32 v[68:69], v[36:37], v[68:69] op_sel:[1,0]
	v_pk_mul_f32 v[36:37], v[36:37], v[66:67] op_sel:[1,0]
	v_pk_fma_f32 v[38:39], v[98:99], v[38:39], v[102:103]
	v_pk_fma_f32 v[36:37], v[34:35], v[36:37], v[94:95]
	v_cvt_pk_bf16_f32 v64, v64, v65
	v_pk_fma_f32 v[66:67], v[32:33], v[68:69], v[92:93]
	v_cvt_pk_bf16_f32 v38, v38, v39
	v_and_b32_e32 v65, 0xffff0000, v104
	v_cvt_pk_bf16_f32 v39, v66, v67
	v_cvt_pk_bf16_f32 v36, v36, v37
	ds_write_b16 v186, v64
	ds_write_b16_d16_hi v186, v64 offset:272
	ds_write_b16 v186, v38 offset:544
	ds_write_b16_d16_hi v186, v38 offset:816
	ds_write_b16 v186, v39 offset:1088
	ds_write_b16_d16_hi v186, v39 offset:1360
	ds_write_b16 v186, v36 offset:1632
	ds_write_b16_d16_hi v186, v36 offset:1904
	ds_read_b64 v[36:37], v187
	v_lshlrev_b32_e32 v64, 16, v104
	v_lshlrev_b32_e32 v38, 16, v105
	v_and_b32_e32 v39, 0xffff0000, v105
	v_lshlrev_b32_e32 v68, 16, v106
	v_and_b32_e32 v69, 0xffff0000, v106
	v_lshlrev_b32_e32 v66, 16, v107
	v_and_b32_e32 v67, 0xffff0000, v107
	s_waitcnt lgkmcnt(0)
	v_sub_f32_e32 v65, v65, v36
	v_sub_f32_e32 v64, v64, v36
	v_sub_f32_e32 v39, v39, v36
	v_sub_f32_e32 v38, v38, v36
	v_pk_mul_f32 v[64:65], v[36:37], v[64:65] op_sel:[1,0]
	v_sub_f32_e32 v67, v67, v36
	v_sub_f32_e32 v66, v66, v36
	v_sub_f32_e32 v69, v69, v36
	v_sub_f32_e32 v68, v68, v36
	v_pk_mul_f32 v[38:39], v[36:37], v[38:39] op_sel:[1,0]
	v_pk_fma_f32 v[64:65], v[96:97], v[64:65], v[100:101]
	v_pk_mul_f32 v[68:69], v[36:37], v[68:69] op_sel:[1,0]
	v_pk_mul_f32 v[36:37], v[36:37], v[66:67] op_sel:[1,0]
	v_pk_fma_f32 v[38:39], v[98:99], v[38:39], v[102:103]
	v_pk_fma_f32 v[36:37], v[34:35], v[36:37], v[94:95]
	v_cvt_pk_bf16_f32 v64, v64, v65
	s_and_b64 vcc, exec, s[4:5]
	v_pk_fma_f32 v[66:67], v[32:33], v[68:69], v[92:93]
	v_cvt_pk_bf16_f32 v38, v38, v39
	s_nop 0
	v_cvt_pk_bf16_f32 v39, v66, v67
	v_cvt_pk_bf16_f32 v36, v36, v37
	ds_write_b16 v188, v64
	ds_write_b16_d16_hi v188, v64 offset:272
	ds_write_b16 v188, v38 offset:544
	ds_write_b16_d16_hi v188, v38 offset:816
	ds_write_b16 v188, v39 offset:1088
	ds_write_b16_d16_hi v188, v39 offset:1360
	ds_write_b16 v188, v36 offset:1632
	ds_write_b16_d16_hi v188, v36 offset:1904
	s_cbranch_vccnz .LBB0_755
	ds_read_b64 v[36:37], v189
	v_lshlrev_b32_e32 v64, 16, v0
	v_and_b32_e32 v65, 0xffff0000, v0
	v_lshlrev_b32_e32 v38, 16, v1
	v_and_b32_e32 v39, 0xffff0000, v1
	v_lshlrev_b32_e32 v68, 16, v2
	v_and_b32_e32 v69, 0xffff0000, v2
	v_lshlrev_b32_e32 v66, 16, v3
	v_and_b32_e32 v67, 0xffff0000, v3
	s_waitcnt lgkmcnt(0)
	v_sub_f32_e32 v65, v65, v36
	v_sub_f32_e32 v64, v64, v36
	v_sub_f32_e32 v39, v39, v36
	v_sub_f32_e32 v38, v38, v36
	v_pk_mul_f32 v[64:65], v[36:37], v[64:65] op_sel:[1,0]
	v_sub_f32_e32 v67, v67, v36
	v_sub_f32_e32 v66, v66, v36
	v_sub_f32_e32 v69, v69, v36
	v_sub_f32_e32 v68, v68, v36
	v_pk_mul_f32 v[38:39], v[36:37], v[38:39] op_sel:[1,0]
	v_pk_fma_f32 v[64:65], v[96:97], v[64:65], v[100:101]
	v_pk_mul_f32 v[68:69], v[36:37], v[68:69] op_sel:[1,0]
	v_pk_mul_f32 v[36:37], v[36:37], v[66:67] op_sel:[1,0]
	v_pk_fma_f32 v[38:39], v[98:99], v[38:39], v[102:103]
	v_pk_fma_f32 v[36:37], v[34:35], v[36:37], v[94:95]
	v_cvt_pk_bf16_f32 v64, v64, v65
	v_pk_fma_f32 v[66:67], v[32:33], v[68:69], v[92:93]
	v_cvt_pk_bf16_f32 v38, v38, v39
	v_and_b32_e32 v65, 0xffff0000, v4
	v_cvt_pk_bf16_f32 v39, v66, v67
	v_cvt_pk_bf16_f32 v36, v36, v37
	ds_write_b16 v190, v64
	ds_write_b16_d16_hi v190, v64 offset:272
	ds_write_b16 v190, v38 offset:544
	ds_write_b16_d16_hi v190, v38 offset:816
	ds_write_b16 v190, v39 offset:1088
	ds_write_b16_d16_hi v190, v39 offset:1360
	ds_write_b16 v190, v36 offset:1632
	ds_write_b16_d16_hi v190, v36 offset:1904
	ds_read_b64 v[36:37], v191
	v_lshlrev_b32_e32 v64, 16, v4
	v_lshlrev_b32_e32 v38, 16, v5
	v_and_b32_e32 v39, 0xffff0000, v5
	v_lshlrev_b32_e32 v68, 16, v6
	v_and_b32_e32 v69, 0xffff0000, v6
	v_lshlrev_b32_e32 v66, 16, v7
	v_and_b32_e32 v67, 0xffff0000, v7
	s_waitcnt lgkmcnt(0)
	v_sub_f32_e32 v39, v39, v36
	v_sub_f32_e32 v38, v38, v36
	v_sub_f32_e32 v65, v65, v36
	v_sub_f32_e32 v64, v64, v36
	v_sub_f32_e32 v67, v67, v36
	v_sub_f32_e32 v66, v66, v36
	v_sub_f32_e32 v69, v69, v36
	v_sub_f32_e32 v68, v68, v36
	v_pk_mul_f32 v[64:65], v[36:37], v[64:65] op_sel:[1,0]
	v_pk_mul_f32 v[38:39], v[36:37], v[38:39] op_sel:[1,0]
	v_pk_mul_f32 v[68:69], v[36:37], v[68:69] op_sel:[1,0]
	v_pk_mul_f32 v[36:37], v[36:37], v[66:67] op_sel:[1,0]
	v_pk_fma_f32 v[64:65], v[96:97], v[64:65], v[100:101]
	v_pk_fma_f32 v[34:35], v[34:35], v[36:37], v[94:95]
	v_pk_fma_f32 v[32:33], v[32:33], v[68:69], v[92:93]
	v_cvt_pk_bf16_f32 v36, v64, v65
	v_pk_fma_f32 v[38:39], v[98:99], v[38:39], v[102:103]
	s_nop 0
	v_cvt_pk_bf16_f32 v37, v38, v39
	v_cvt_pk_bf16_f32 v32, v32, v33
	v_cvt_pk_bf16_f32 v33, v34, v35
	ds_write_b16 v192, v36
	ds_write_b16_d16_hi v192, v36 offset:272
	ds_write_b16 v192, v37 offset:544
	ds_write_b16_d16_hi v192, v37 offset:816
	ds_write_b16 v192, v32 offset:1088
	ds_write_b16_d16_hi v192, v32 offset:1360
	ds_write_b16 v192, v33 offset:1632
	ds_write_b16_d16_hi v192, v33 offset:1904
.LBB0_755:
	s_waitcnt vmcnt(2)
	ds_write_b128 v228, v[224:227]
	s_waitcnt lgkmcnt(0)
	s_barrier
	ds_read_b128 v[88:91], v229 offset:0
	ds_read_b128 v[76:79], v229 offset:64
	ds_read_b128 v[80:83], v229 offset:128
	ds_read_b128 v[72:75], v229 offset:192
	ds_read_b32 v180, v223 offset:3072
	global_load_dwordx4 v[116:119], v[112:113], off offset:1792
	s_nop 0
	global_load_dwordx4 v[112:115], v[114:115], off offset:1792
	s_and_b64 vcc, exec, s[4:5]
	s_cbranch_vccnz .LBB0_757
	v_lshlrev_b64 v[0:1], 11, v[152:153]
	v_lshl_add_u64 v[0:1], v[122:123], 0, v[0:1]
	global_load_dwordx4 v[0:3], v[0:1], off offset:1792

; #define LAS __attribute__((address_space(3)))
; __global__ void __launch_bounds__(NTHR, 2) fwd_megakernel(Args args) {
;     ...
;                 if (h + 1 < 8) SGU_PREFETCH(h + 1);
;                 f32x4 a0 = (f32x4){0.f, 0.f, 0.f, 0.f}, a1 = a0;
; #pragma unroll
;                 for (int ks = 0; ks < 4; ++ks) if (ks < nk) {
;                     const int r0 = 16 * (2 * nq) + fr, r1 = r0 + 16, q = ks * 4 + fq;
;                     const bf16x8 x0 = *(const LAS bf16x8*)(Bc + r0 * LDB + ((q ^ ((r0 >> 3) & 15)) * 8)), x1 = *(const LAS bf16x8*)(Bc + r1 * LDB + ((q ^ ((r1 >> 3) & 15)) * 8));
;                     a0 = __builtin_amdgcn_mfma_f32_16x16x32_bf16(x0, cw[ks], a0, 0, 0, 0); a1 = __builtin_amdgcn_mfma_f32_16x16x32_bf16(x1, cw[ks], a1, 0, 0, 0);
;                 }
.LBB0_759:
	s_nop 0
	ds_read_b128 v[96:99], v203 offset:3600
	ds_read_b128 v[104:107], v203 offset:3584
	ds_read_b128 v[100:103], v203 offset:7696
	ds_read_b128 v[108:111], v203 offset:7680
	v_add_co_u32_e32 v32, vcc, 0x38000, v148
	s_waitcnt vmcnt(5)
	v_mov_b64_e32 v[36:37], v[80:81]
	v_addc_co_u32_e32 v33, vcc, 0, v149, vcc
	global_load_dwordx4 v[224:227], v[218:219], off
	v_lshl_add_u64 v[218:219], v[218:219], 0, s[100:101]
	s_nop 0
	s_and_b64 vcc, exec, s[4:5]
	v_mov_b64_e32 v[38:39], v[82:83]
	s_cbranch_vccnz .LBB0_761
	v_add_co_u32_e32 v32, vcc, 0x38000, v148
	s_nop 1
	v_addc_co_u32_e32 v33, vcc, 0, v149, vcc
	s_nop 0
.LBB0_761:
	v_mov_b64_e32 v[32:33], v[72:73]
	s_and_b64 vcc, exec, s[4:5]
	v_mov_b64_e32 v[34:35], v[74:75]
	s_cbranch_vccnz .LBB0_763
	v_add_co_u32_e32 v32, vcc, 0x38000, v148
	s_nop 1
	v_addc_co_u32_e32 v33, vcc, 0, v149, vcc
	s_nop 0
.LBB0_763:
	ds_read_b128 v[64:67], v193
	ds_read_b128 v[68:71], v194
	s_and_b64 vcc, exec, s[4:5]
	s_waitcnt lgkmcnt(1)
	v_mfma_f32_16x16x32_bf16 v[64:67], v[64:67], v[88:91], 0
	ds_read_b128 v[208:211], v196
	s_waitcnt lgkmcnt(1)
	v_mfma_f32_16x16x32_bf16 v[204:207], v[68:71], v[88:91], 0
	ds_read_b128 v[68:71], v195
	s_nop 0
	global_load_dwordx2 v[146:147], v[150:151], off offset:1792
	global_load_dwordx2 v[90:91], v[150:151], off offset:1824
	s_waitcnt lgkmcnt(0)
	v_mfma_f32_16x16x32_bf16 v[68:71], v[68:71], v[76:79], v[64:67]
	v_mfma_f32_16x16x32_bf16 v[64:67], v[208:211], v[76:79], v[204:207]
	s_cbranch_vccnz .LBB0_765
	ds_read_b128 v[76:79], v197
	ds_read_b128 v[148:151], v198
	s_waitcnt lgkmcnt(1)
	v_mfma_f32_16x16x32_bf16 v[68:71], v[76:79], v[80:83], v[68:71]
	s_waitcnt lgkmcnt(0)
	v_mfma_f32_16x16x32_bf16 v[64:67], v[148:151], v[80:83], v[64:67]

; #define LAS __attribute__((address_space(3)))
; __device__ __forceinline__ unsigned cvt_pk_bf16(float lo, float hi) { unsigned r; asm volatile("v_cvt_pk_bf16_f32 %0, %1, %2" : "=v"(r) : "v"(lo), "v"(hi)); return r; }
; __device__ __forceinline__ float bf_lo(unsigned u) { return __uint_as_float(u << 16); }
; __device__ __forceinline__ float bf_hi(unsigned u) { return __uint_as_float(u & 0xffff0000u); }
; __global__ void __launch_bounds__(NTHR, 2) fwd_megakernel(Args args) {
;     ...
;                 LAS bf16_t* Bc = Bt + (h & 1) * (128 * LDB);
; #pragma unroll
;                 for (int k = 0; k < 4; ++k) if (k < nk) { const int j = jb + 32 * k; const u32x4 v = pv[k]; const f32x2 ms = st[j];
;                     const f32x4 x0 = (f32x4){bf_lo(v.x), bf_hi(v.x), bf_lo(v.y), bf_hi(v.y)}, x1 = (f32x4){bf_lo(v.z), bf_hi(v.z), bf_lo(v.w), bf_hi(v.w)};
;                     const f32x4 y0 = (x0 - ms.x) * ms.y * pg0 + pb0, y1 = (x1 - ms.x) * ms.y * pg1 + pb1;
;                     LAS bf16_t* d = Bc + (c8 * 8) * LDB + (j ^ (8 * c8));
;                     const unsigned p0 = cvt_pk_bf16(y0[0], y0[1]), p1 = cvt_pk_bf16(y0[2], y0[3]), p2 = cvt_pk_bf16(y1[0], y1[1]), p3 = cvt_pk_bf16(y1[2], y1[3]);
;                     d[0 * LDB] = (bf16_t)(p0 & 0xffffu); d[1 * LDB] = (bf16_t)(p0 >> 16); d[2 * LDB] = (bf16_t)(p1 & 0xffffu); d[3 * LDB] = (bf16_t)(p1 >> 16);
;                     d[4 * LDB] = (bf16_t)(p2 & 0xffffu); d[5 * LDB] = (bf16_t)(p2 >> 16); d[6 * LDB] = (bf16_t)(p3 & 0xffffu); d[7 * LDB] = (bf16_t)(p3 >> 16); }
.LBB0_767:
	ds_read_b64 v[72:73], v181
	s_waitcnt vmcnt(4)
	v_lshlrev_b32_e32 v76, 16, v116
	v_and_b32_e32 v77, 0xffff0000, v116
	v_lshlrev_b32_e32 v74, 16, v117
	v_and_b32_e32 v75, 0xffff0000, v117
	v_lshlrev_b32_e32 v80, 16, v118
	v_and_b32_e32 v81, 0xffff0000, v118
	v_lshlrev_b32_e32 v78, 16, v119
	v_and_b32_e32 v79, 0xffff0000, v119
	s_waitcnt lgkmcnt(0)
	v_sub_f32_e32 v77, v77, v72
	v_sub_f32_e32 v76, v76, v72
	v_sub_f32_e32 v75, v75, v72
	v_sub_f32_e32 v74, v74, v72
	v_pk_mul_f32 v[76:77], v[72:73], v[76:77] op_sel:[1,0]
	v_sub_f32_e32 v79, v79, v72
	v_sub_f32_e32 v78, v78, v72
	v_sub_f32_e32 v81, v81, v72
	v_sub_f32_e32 v80, v80, v72
	v_pk_mul_f32 v[74:75], v[72:73], v[74:75] op_sel:[1,0]
	s_waitcnt vmcnt(3)
	v_pk_fma_f32 v[76:77], v[104:105], v[76:77], v[108:109]
	v_pk_mul_f32 v[80:81], v[72:73], v[80:81] op_sel:[1,0]
	v_pk_mul_f32 v[72:73], v[72:73], v[78:79] op_sel:[1,0]
	v_pk_fma_f32 v[74:75], v[106:107], v[74:75], v[110:111]
	v_pk_fma_f32 v[72:73], v[98:99], v[72:73], v[102:103]
	v_cvt_pk_bf16_f32 v76, v76, v77
	v_pk_fma_f32 v[78:79], v[96:97], v[80:81], v[100:101]
	v_cvt_pk_bf16_f32 v74, v74, v75
	v_and_b32_e32 v77, 0xffff0000, v112
	v_cvt_pk_bf16_f32 v75, v78, v79
	v_cvt_pk_bf16_f32 v72, v72, v73
	ds_write_b16 v186, v76 offset:34816
	ds_write_b16_d16_hi v186, v76 offset:35088
	ds_write_b16 v186, v74 offset:35360
	ds_write_b16_d16_hi v186, v74 offset:35632
	ds_write_b16 v186, v75 offset:35904
	ds_write_b16_d16_hi v186, v75 offset:36176
	ds_write_b16 v186, v72 offset:36448
	ds_write_b16_d16_hi v186, v72 offset:36720
	ds_read_b64 v[72:73], v187
	v_lshlrev_b32_e32 v76, 16, v112
	v_lshlrev_b32_e32 v74, 16, v113
	v_and_b32_e32 v75, 0xffff0000, v113
	v_lshlrev_b32_e32 v80, 16, v114
	v_and_b32_e32 v81, 0xffff0000, v114
	v_lshlrev_b32_e32 v78, 16, v115
	v_and_b32_e32 v79, 0xffff0000, v115
	s_waitcnt lgkmcnt(0)
	v_sub_f32_e32 v77, v77, v72
	v_sub_f32_e32 v76, v76, v72
	v_sub_f32_e32 v75, v75, v72
	v_sub_f32_e32 v74, v74, v72
	v_pk_mul_f32 v[76:77], v[72:73], v[76:77] op_sel:[1,0]
	v_sub_f32_e32 v79, v79, v72
	v_sub_f32_e32 v78, v78, v72
	v_sub_f32_e32 v81, v81, v72
	v_sub_f32_e32 v80, v80, v72
	v_pk_mul_f32 v[74:75], v[72:73], v[74:75] op_sel:[1,0]
	v_pk_fma_f32 v[76:77], v[104:105], v[76:77], v[108:109]
	v_pk_mul_f32 v[80:81], v[72:73], v[80:81] op_sel:[1,0]
	v_pk_mul_f32 v[72:73], v[72:73], v[78:79] op_sel:[1,0]
	v_pk_fma_f32 v[74:75], v[106:107], v[74:75], v[110:111]
	v_pk_fma_f32 v[72:73], v[98:99], v[72:73], v[102:103]
	v_cvt_pk_bf16_f32 v76, v76, v77
	s_and_b64 vcc, exec, s[4:5]
	v_pk_fma_f32 v[78:79], v[96:97], v[80:81], v[100:101]
	v_cvt_pk_bf16_f32 v74, v74, v75
	s_nop 0
	v_cvt_pk_bf16_f32 v75, v78, v79
	v_cvt_pk_bf16_f32 v72, v72, v73
	ds_write_b16 v188, v76 offset:34816
	ds_write_b16_d16_hi v188, v76 offset:35088
	ds_write_b16 v188, v74 offset:35360
	ds_write_b16_d16_hi v188, v74 offset:35632
	ds_write_b16 v188, v75 offset:35904
	ds_write_b16_d16_hi v188, v75 offset:36176
	ds_write_b16 v188, v72 offset:36448
	ds_write_b16_d16_hi v188, v72 offset:36720
	s_cbranch_vccnz .LBB0_769
	ds_read_b64 v[72:73], v189
	v_lshlrev_b32_e32 v76, 16, v0
	v_and_b32_e32 v77, 0xffff0000, v0
	v_lshlrev_b32_e32 v74, 16, v1
	v_and_b32_e32 v75, 0xffff0000, v1
	v_lshlrev_b32_e32 v80, 16, v2
	v_and_b32_e32 v81, 0xffff0000, v2
	v_lshlrev_b32_e32 v78, 16, v3
	v_and_b32_e32 v79, 0xffff0000, v3
	s_waitcnt lgkmcnt(0)
	v_sub_f32_e32 v77, v77, v72
	v_sub_f32_e32 v76, v76, v72
	v_sub_f32_e32 v75, v75, v72
	v_sub_f32_e32 v74, v74, v72
	v_pk_mul_f32 v[76:77], v[72:73], v[76:77] op_sel:[1,0]
	v_sub_f32_e32 v79, v79, v72
	v_sub_f32_e32 v78, v78, v72
	v_sub_f32_e32 v81, v81, v72
	v_sub_f32_e32 v80, v80, v72
	v_pk_mul_f32 v[74:75], v[72:73], v[74:75] op_sel:[1,0]
	v_pk_fma_f32 v[76:77], v[104:105], v[76:77], v[108:109]
	v_pk_mul_f32 v[80:81], v[72:73], v[80:81] op_sel:[1,0]
	v_pk_mul_f32 v[72:73], v[72:73], v[78:79] op_sel:[1,0]
	v_pk_fma_f32 v[74:75], v[106:107], v[74:75], v[110:111]
	v_pk_fma_f32 v[72:73], v[98:99], v[72:73], v[102:103]
	v_cvt_pk_bf16_f32 v76, v76, v77
	v_pk_fma_f32 v[78:79], v[96:97], v[80:81], v[100:101]
	v_cvt_pk_bf16_f32 v74, v74, v75
	v_and_b32_e32 v77, 0xffff0000, v4
	v_cvt_pk_bf16_f32 v75, v78, v79
	v_cvt_pk_bf16_f32 v72, v72, v73
	ds_write_b16 v190, v76 offset:34816
	ds_write_b16_d16_hi v190, v76 offset:35088
	ds_write_b16 v190, v74 offset:35360
	ds_write_b16_d16_hi v190, v74 offset:35632
	ds_write_b16 v190, v75 offset:35904
	ds_write_b16_d16_hi v190, v75 offset:36176
	ds_write_b16 v190, v72 offset:36448
	ds_write_b16_d16_hi v190, v72 offset:36720
	ds_read_b64 v[72:73], v191
	v_lshlrev_b32_e32 v76, 16, v4
	v_lshlrev_b32_e32 v74, 16, v5
	v_and_b32_e32 v75, 0xffff0000, v5
	v_lshlrev_b32_e32 v80, 16, v6
	v_and_b32_e32 v81, 0xffff0000, v6
	v_lshlrev_b32_e32 v78, 16, v7
	v_and_b32_e32 v79, 0xffff0000, v7
	s_waitcnt lgkmcnt(0)
	v_sub_f32_e32 v77, v77, v72
	v_sub_f32_e32 v76, v76, v72
	v_sub_f32_e32 v75, v75, v72
	v_sub_f32_e32 v74, v74, v72
	v_pk_mul_f32 v[76:77], v[72:73], v[76:77] op_sel:[1,0]
	v_sub_f32_e32 v79, v79, v72
	v_sub_f32_e32 v78, v78, v72
	v_sub_f32_e32 v81, v81, v72
	v_sub_f32_e32 v80, v80, v72
	v_pk_mul_f32 v[74:75], v[72:73], v[74:75] op_sel:[1,0]
	v_pk_fma_f32 v[76:77], v[104:105], v[76:77], v[108:109]
	v_pk_mul_f32 v[80:81], v[72:73], v[80:81] op_sel:[1,0]
	v_pk_mul_f32 v[72:73], v[72:73], v[78:79] op_sel:[1,0]
	v_pk_fma_f32 v[74:75], v[106:107], v[74:75], v[110:111]
	v_pk_fma_f32 v[72:73], v[98:99], v[72:73], v[102:103]
	v_cvt_pk_bf16_f32 v76, v76, v77
	v_pk_fma_f32 v[78:79], v[96:97], v[80:81], v[100:101]
	v_cvt_pk_bf16_f32 v74, v74, v75
	s_nop 0
	v_cvt_pk_bf16_f32 v75, v78, v79
	v_cvt_pk_bf16_f32 v72, v72, v73
	ds_write_b16 v192, v76 offset:34816
	ds_write_b16_d16_hi v192, v76 offset:35088
	ds_write_b16 v192, v74 offset:35360
	ds_write_b16_d16_hi v192, v74 offset:35632
	ds_write_b16 v192, v75 offset:35904
	ds_write_b16_d16_hi v192, v75 offset:36176
	ds_write_b16 v192, v72 offset:36448
	ds_write_b16_d16_hi v192, v72 offset:36720
; #define LAS __attribute__((address_space(3)))
; __global__ void __launch_bounds__(NTHR, 2) fwd_megakernel(Args args) {
;     ...
;                 const u32x2 u0 = pu0, u1 = pu1; const float bs = pbs;
;                 __syncthreads();
;                 if (h + 1 < 8) SGU_PREFETCH(h + 1);
;                 f32x4 a0 = (f32x4){0.f, 0.f, 0.f, 0.f}, a1 = a0;
; #pragma unroll
;                 for (int ks = 0; ks < 4; ++ks) if (ks < nk) {
;                     const int r0 = 16 * (2 * nq) + fr, r1 = r0 + 16, q = ks * 4 + fq;
;                     const bf16x8 x0 = *(const LAS bf16x8*)(Bc + r0 * LDB + ((q ^ ((r0 >> 3) & 15)) * 8)), x1 = *(const LAS bf16x8*)(Bc + r1 * LDB + ((q ^ ((r1 >> 3) & 15)) * 8));
;                     a0 = __builtin_amdgcn_mfma_f32_16x16x32_bf16(x0, cw[ks], a0, 0, 0, 0); a1 = __builtin_amdgcn_mfma_f32_16x16x32_bf16(x1, cw[ks], a1, 0, 0, 0);
;                 }
.LBB0_769:
	s_waitcnt vmcnt(2)
	ds_write_b128 v228, v[224:227] offset:8704
	s_waitcnt lgkmcnt(0)
	s_barrier
	ds_read_b128 v[92:95], v229 offset:8704
	ds_read_b128 v[84:87], v229 offset:8768
	ds_read_b128 v[36:39], v229 offset:8832
	ds_read_b128 v[32:35], v229 offset:8896
	ds_read_b32 v88, v223 offset:3584
	ds_read_b128 v[72:75], v193 offset:34816
	ds_read_b128 v[76:79], v194 offset:34816
	ds_read_b128 v[80:83], v195 offset:34816
	ds_read_b128 v[96:99], v196 offset:34816
	s_waitcnt vmcnt(4) lgkmcnt(3)
	v_mfma_f32_16x16x32_bf16 v[72:75], v[72:75], v[92:95], 0
	s_and_b64 vcc, exec, s[4:5]
	s_waitcnt lgkmcnt(2)
	v_mfma_f32_16x16x32_bf16 v[92:95], v[76:79], v[92:95], 0
	s_waitcnt vmcnt(3) lgkmcnt(1)
	v_mfma_f32_16x16x32_bf16 v[76:79], v[80:83], v[84:87], v[72:75]
	s_waitcnt lgkmcnt(0)
	v_mfma_f32_16x16x32_bf16 v[72:75], v[96:99], v[84:87], v[92:95]
	s_cbranch_vccnz .LBB0_771
	ds_read_b128 v[80:83], v197 offset:34816
	ds_read_b128 v[84:87], v198 offset:34816
	s_waitcnt lgkmcnt(1)
	v_mfma_f32_16x16x32_bf16 v[76:79], v[80:83], v[36:39], v[76:79]
	s_waitcnt lgkmcnt(0)
	v_mfma_f32_16x16x32_bf16 v[72:75], v[84:87], v[36:39], v[72:75]
